# XCD-aligned work mapping: GEMM tiles permuted so each XCD owns 4 token panels (all column panels), norm rows follow the same XCD ownership
# speedup vs baseline: 1.0328x; 1.0174x over previous
.LBB0_34:
	s_add_i32 s3, s70, -1
	s_mul_hi_i32 s4, s3, 0x92492493
	s_add_i32 s4, s4, s3
	s_lshr_b32 s5, s4, 31
	s_ashr_i32 s4, s4, 2
	s_add_i32 s79, s4, s5
	s_mul_i32 s4, s79, 7
	s_sub_i32 s80, s3, s4
	s_ashr_i32 s4, s79, 1
	v_writelane_b32 v239, s4, 47
	s_bitcmp1_b32 s79, 0
	s_mul_hi_i32 s3, s79, 0x12000
	v_writelane_b32 v239, s5, 48
	s_cselect_b64 s[4:5], -1, 0
	v_writelane_b32 v239, s4, 49
	s_mov_b64 s[66:67], 0
	s_mov_b64 s[84:85], 0
	v_writelane_b32 v239, s5, 50
	s_mul_i32 s4, s79, 0x12000
	v_readlane_b32 s6, v239, 29
	v_readlane_b32 s7, v239, 30
	s_add_u32 s4, s6, s4
	s_addc_u32 s5, s7, s3
	v_writelane_b32 v239, s4, 51
	s_mov_b64 s[6:7], s[70:71]
	s_cmp_lt_i32 s80, 3
	v_writelane_b32 v239, s5, 52
	s_mov_b64 s[4:5], -1
	v_writelane_b32 v239, s4, 53
	s_nop 1
	v_writelane_b32 v239, s5, 54
	v_writelane_b32 v239, s6, 55
	v_writelane_b32 v239, s7, 56
	s_cbranch_scc1 .LBB0_160
	s_cmp_gt_i32 s80, 3
	s_cbranch_scc0 .LBB0_63
	s_cmp_gt_i32 s80, 4
	s_cbranch_scc0 .LBB0_64
	s_cmp_eq_u32 s80, 5
	s_mov_b64 s[84:85], -1
	s_cbranch_scc0 .LBB0_81
	v_readlane_b32 s4, v239, 29
	v_readlane_b32 s5, v239, 30
	s_add_u32 s15, s4, 0x2700000
	s_addc_u32 s33, s5, 0
	s_cmpk_gt_i32 s78, 0x2bf
	v_readfirstlane_b32 s14, v210
	s_cbranch_scc1 .LBB0_66
	v_lshlrev_b32_e32 v0, 4, v210
	v_add_u32_e32 v1, 0x2000, v0
	v_ashrrev_i32_e32 v2, 31, v1
	v_lshrrev_b32_e32 v2, 22, v2
	v_add_u32_e32 v2, v1, v2
	v_ashrrev_i32_e32 v8, 10, v2
	v_mul_i32_i24_e32 v2, 0x400, v8
	v_sub_u32_e32 v1, v1, v2
	v_lshrrev_b32_e32 v2, 4, v1
	v_bitop3_b32 v1, v2, v1, 32 bitop3:0x6c
	v_writelane_b32 v239, s80, 59
	v_ashrrev_i32_e32 v2, 31, v1
	v_readlane_b32 s4, v239, 29
	v_lshrrev_b32_e32 v2, 26, v2
	v_readlane_b32 s5, v239, 30
	s_add_u32 s10, s4, 0x8900000
	v_add_u32_e32 v2, v1, v2
	v_lshlrev_b32_e32 v3, 3, v8
	s_addc_u32 s11, s5, 0
	s_mul_i32 s4, s79, 0xb00000
	v_ashrrev_i32_e32 v9, 6, v2
	v_and_b32_e32 v3, -16, v3
	s_mul_hi_i32 s3, s79, 0xb00000
	s_add_u32 s34, s15, s4
	v_add_u32_e32 v3, v9, v3
	s_addc_u32 s35, s33, s3
	v_and_b32_e32 v4, 3, v9
	s_mov_b32 s3, 0x1fffe0
	v_lshrrev_b32_e32 v5, 2, v3
	v_lshlrev_b32_e32 v6, 1, v3
	v_and_b32_e32 v2, 0xc0, v2
	v_and_or_b32 v4, v3, s3, v4
	v_and_b32_e32 v5, 4, v5
	v_and_b32_e32 v6, 24, v6
	v_sub_u32_e32 v1, v1, v2
	v_or3_b32 v4, v4, v5, v6
	v_lshlrev_b32_e32 v5, 5, v8
	v_ashrrev_i16_sdwa v1, v198, sext(v1) dst_sel:DWORD dst_unused:UNUSED_PAD src0_sel:DWORD src1_sel:BYTE_0
	v_and_b32_e32 v5, 32, v5
	v_bfe_i32 v10, v1, 0, 16
	v_add_lshl_u32 v1, v5, v10, 1
	v_lshl_add_u32 v160, v4, 11, v1
	v_lshl_add_u32 v162, v3, 11, v1
	v_bfe_i32 v1, v210, 27, 1
	v_lshrrev_b32_e32 v1, 22, v1
	v_add_u32_e32 v1, v0, v1
	v_and_b32_e32 v1, 0xfffffc00, v1
	v_sub_u32_e32 v0, v0, v1
	v_lshrrev_b32_e32 v1, 4, v0
	v_ashrrev_i32_e32 v2, 31, v210
	v_bitop3_b32 v0, v1, v0, 32 bitop3:0x6c
	v_lshrrev_b32_e32 v2, 26, v2
	v_ashrrev_i32_e32 v1, 31, v0
	v_add_u32_e32 v2, v210, v2
	v_lshrrev_b32_e32 v1, 26, v1
	v_ashrrev_i32_e32 v12, 6, v2
	v_add_u32_e32 v1, v0, v1
	v_lshlrev_b32_e32 v2, 3, v12
	v_ashrrev_i32_e32 v11, 6, v1
	v_and_b32_e32 v2, -16, v2
	v_add_u32_e32 v2, v11, v2
	v_and_b32_e32 v3, 3, v11
	v_and_or_b32 v3, v2, s3, v3
	s_lshr_b32 s99, s78, 5
	s_cmp_gt_u32 s99, 10
	s_cselect_b32 s98, 0xfffffd41, 0
	s_lshl_b32 s99, s99, 6
	s_add_i32 s98, s98, s99
	s_and_b32 s99, s78, 1
	s_lshl_b32 s99, s99, 5
	s_add_i32 s98, s98, s99
	s_and_b32 s99, s78, 0x18
	s_add_i32 s98, s98, s99
	s_and_b32 s99, s78, 6
	s_add_i32 s98, s98, s99
	s_ashr_i32 s3, s98, 31
	s_lshr_b32 s3, s3, 29
	v_writelane_b32 v238, s15, 6
	s_add_i32 s3, s98, s3
	v_writelane_b32 v238, s33, 7
	s_ashr_i32 s33, s14, 6
	s_and_b32 s4, s3, -8
	s_ashr_i32 s15, s14, 8
	s_lshl_b32 s13, s33, 10
	s_sub_i32 s4, s98, s4
	s_cmp_lt_i32 s4, 0
	s_movk_i32 s5, 0x59
	s_cselect_b32 s5, s5, 0x58
	s_mul_i32 s4, s4, s5
	s_ashr_i32 s3, s3, 3
	s_add_i32 s4, s4, s3
	s_mul_hi_i32 s3, s4, 0xd1745d17
	s_lshr_b32 s5, s3, 31
	s_ashr_i32 s3, s3, 7
	s_add_i32 s8, s3, s5
	s_mul_hi_i32 s3, s4, 0x2e8ba2e9
	s_lshr_b32 s5, s3, 31
	s_ashr_i32 s3, s3, 7
	s_add_i32 s3, s3, s5
	s_mulk_i32 s3, 0x2c0
	s_sub_i32 s3, s4, s3
	s_sext_i32_i16 s4, s3
	s_mulk_i32 s4, 0xba3
	s_lshr_b32 s5, s4, 31
	s_ashr_i32 s4, s4, 19
	s_add_i32 s4, s4, s5
	s_lshl_b32 s5, s4, 3
	s_mulk_i32 s4, 0xb0
	s_sub_i32 s3, s3, s4
	s_sext_i32_i16 s4, s3
	s_bfe_u32 s4, s4, 0x3001c
	v_readlane_b32 s6, v240, 62
	s_add_i32 s4, s3, s4
	s_sext_i32_i16 s6, s4
	s_and_b32 s4, s4, 0xfff8
	s_sub_i32 s3, s3, s4
	v_readlane_b32 s7, v240, 63
	s_sext_i32_i16 s3, s3
	s_mov_b32 s9, s7
	s_lshr_b32 s12, s6, 3
	s_add_i32 s6, s5, s3
	s_ashr_i32 s7, s6, 31
	s_mov_b32 s3, s9
	v_writelane_b32 v240, s2, 62
	s_lshl_b64 s[8:9], s[8:9], 11
	s_lshl_b64 s[4:5], s[6:7], 19
	v_writelane_b32 v240, s3, 63
	s_add_u32 s3, s10, s8
	s_addc_u32 s7, s11, s9
	s_add_u32 s4, s3, s4
	s_mov_b32 vcc_lo, s10
	v_writelane_b32 v238, s11, 3
	s_addc_u32 s5, s7, s5
	s_bfe_i64 s[10:11], s[12:13], 0x100000
	v_lshrrev_b32_e32 v4, 2, v2
	v_lshlrev_b32_e32 v5, 1, v2
	v_and_b32_e32 v1, 0xc0, v1
	s_lshl_b64 s[10:11], s[10:11], 19
	v_and_b32_e32 v4, 4, v4
	v_and_b32_e32 v5, 24, v5
	v_sub_u32_e32 v0, v0, v1
	s_add_u32 s3, s34, s8
	v_or3_b32 v3, v3, v4, v5
	v_lshlrev_b32_e32 v4, 5, v12
	v_ashrrev_i16_sdwa v0, v198, sext(v0) dst_sel:DWORD dst_unused:UNUSED_PAD src0_sel:DWORD src1_sel:BYTE_0
	s_addc_u32 s7, s35, s9
	v_and_b32_e32 v4, 32, v4
	v_bfe_i32 v13, v0, 0, 16
	s_add_u32 s8, s3, s10
	v_add_lshl_u32 v0, v4, v13, 1
	s_addc_u32 s9, s7, s11
	s_add_i32 s10, s13, 0
	v_lshl_add_u32 v164, v3, 11, v0
	s_add_i32 m0, s10, 0x10000
	v_writelane_b32 v238, s34, 11
	global_load_lds_dwordx4 v164, s[8:9]
	s_add_i32 m0, s10, 0x12000
	s_add_u32 s34, s8, 0x40000
	v_writelane_b32 v238, s35, 2
	global_load_lds_dwordx4 v160, s[8:9]
	s_addc_u32 s35, s9, 0
	s_add_i32 m0, s10, 0x14000
	s_add_i32 s11, s10, 0x2000
	global_load_lds_dwordx4 v164, s[34:35]
	s_add_i32 m0, s10, 0x16000
	v_lshl_add_u32 v166, v2, 11, v0
	v_bfe_u32 v228, v166, 11, 6
	v_lshlrev_b32_e32 v229, 2, v228
	v_lshrrev_b32_e32 v228, 4, v228
	v_or_b32_e32 v228, v229, v228
	v_and_b32_e32 v228, 63, v228
	v_and_b32_e32 v166, 0xfffe07ff, v166
	v_lshl_or_b32 v166, v228, 11, v166
	v_bfe_u32 v228, v162, 11, 6
	v_lshlrev_b32_e32 v229, 2, v228
	v_lshrrev_b32_e32 v228, 4, v228
	v_or_b32_e32 v228, v229, v228
	v_and_b32_e32 v228, 63, v228
	v_and_b32_e32 v162, 0xfffe07ff, v162
	v_lshl_or_b32 v162, v228, 11, v162
	global_load_lds_dwordx4 v160, s[34:35]
	s_mov_b32 m0, s10
	s_add_u32 s34, s4, 0x40000
	global_load_lds_dwordx4 v166, s[4:5]
	s_mov_b32 m0, s11
	s_addc_u32 s35, s5, 0
	s_add_i32 s72, s10, 0x4000
	global_load_lds_dwordx4 v162, s[4:5]
	s_mov_b32 m0, s72
	s_add_i32 s73, s10, 0x6000
	global_load_lds_dwordx4 v166, s[34:35]
	s_mov_b32 m0, s73
	v_mov_b32_e32 v161, v165
	global_load_lds_dwordx4 v162, s[34:35]
	v_mov_b32_e32 v167, v165
	v_mov_b32_e32 v163, v165
	s_cmp_eq_u32 s15, 1
	s_mov_b64 s[68:69], s[58:59]
	v_lshl_add_u64 v[6:7], s[8:9], 0, v[164:165]
	v_lshl_add_u64 v[4:5], s[8:9], 0, v[160:161]
	v_lshl_add_u64 v[0:1], s[4:5], 0, v[166:167]
	s_cselect_b64 s[88:89], -1, 0
	s_cmp_lg_u32 s15, 1
	v_lshl_add_u64 v[2:3], s[4:5], 0, v[162:163]
	s_cbranch_scc1 .LBB0_41
	s_barrier

.LBB0_44:
	s_add_i32 s51, s51, 1
	s_mul_i32 s7, s51, s60
	s_add_i32 s7, s7, s78
	s_cmpk_lt_i32 s7, 0x2c0
	s_cselect_b64 s[82:83], -1, 0
	s_cmpk_gt_i32 s7, 0x2bf
	s_cbranch_scc1 .LBB0_46
	s_lshr_b32 s99, s7, 5
	s_cmp_gt_u32 s99, 10
	s_cselect_b32 s98, 0xfffffd41, 0
	s_lshl_b32 s99, s99, 6
	s_add_i32 s98, s98, s99
	s_and_b32 s99, s7, 1
	s_lshl_b32 s99, s99, 5
	s_add_i32 s98, s98, s99
	s_and_b32 s99, s7, 0x18
	s_add_i32 s98, s98, s99
	s_and_b32 s99, s7, 6
	s_add_i32 s98, s98, s99
	s_mov_b32 s7, s98
	s_ashr_i32 s14, s7, 31
	s_lshr_b32 s14, s14, 29
	s_add_i32 s14, s7, s14
	s_ashr_i32 s15, s14, 3
	s_and_b32 s14, s14, -8
	s_sub_i32 s7, s7, s14
	s_cmp_lt_i32 s7, 0
	s_movk_i32 s14, 0x59
	s_cselect_b32 s14, s14, 0x58
	s_mul_i32 s7, s7, s14
	s_add_i32 s7, s7, s15
	s_mul_hi_i32 s14, s7, 0xd1745d17
	s_lshr_b32 s15, s14, 31
	s_ashr_i32 s14, s14, 7
	s_add_i32 s52, s14, s15
	s_mul_hi_i32 s14, s7, 0x2e8ba2e9
	s_lshr_b32 s15, s14, 31
	s_ashr_i32 s14, s14, 7
	s_add_i32 s14, s14, s15
	s_mulk_i32 s14, 0x2c0
	s_sub_i32 s7, s7, s14
	s_sext_i32_i16 s14, s7
	s_mulk_i32 s14, 0xba3
	s_lshr_b32 s15, s14, 31
	s_ashr_i32 s14, s14, 19
	s_add_i32 s14, s14, s15
	s_lshl_b32 s15, s14, 3
	s_mulk_i32 s14, 0xb0
	s_sub_i32 s7, s7, s14
	s_sext_i32_i16 s14, s7
	s_bfe_u32 s14, s14, 0x3001c
	s_add_i32 s14, s7, s14
	s_sext_i32_i16 s33, s14
	s_and_b32 s14, s14, 0xfff8
	s_sub_i32 s7, s7, s14
	v_readlane_b32 s34, v240, 62
	s_sext_i32_i16 s7, s7
	v_readlane_b32 s35, v240, 63
	s_add_i32 s70, s15, s7
	s_mov_b32 s53, s35
	s_ashr_i32 s71, s70, 31
	s_mov_b32 s7, s35
	s_lshr_b32 s34, s33, 3
	s_ashr_i32 s33, s33, 3
	v_writelane_b32 v240, s6, 62
	s_lshl_b64 s[52:53], s[52:53], 11
	s_lshl_b64 s[14:15], s[70:71], 19
	v_writelane_b32 v240, s7, 63
	s_mov_b32 s71, s33
	s_add_u32 s7, s57, s52
	v_readlane_b32 s33, v238, 3
	s_addc_u32 s33, s33, s53
	s_add_u32 s14, s7, s14
	s_addc_u32 s15, s33, s15
	s_bfe_i64 s[34:35], s[34:35], 0x100000
	s_lshl_b64 s[34:35], s[34:35], 19
	v_readlane_b32 s7, v238, 11
	s_add_u32 s7, s7, s52
	v_readlane_b32 s33, v238, 2
	s_addc_u32 s33, s33, s53
	s_add_u32 s34, s7, s34
	s_addc_u32 s35, s33, s35

.LBB0_82:
	v_readlane_b32 s34, v239, 29
	v_readlane_b32 s35, v239, 30
	s_and_b64 vcc, exec, s[4:5]
	s_cbranch_vccz .LBB0_99
	s_waitcnt lgkmcnt(0)
	s_lshl_b32 s7, s79, 12
	s_add_u32 s18, s18, s7
	s_addc_u32 s19, s19, 0
	v_readlane_b32 s14, v239, 51
	v_readlane_b32 s15, v239, 52
	v_and_b32_e32 v8, 63, v211
	v_lshlrev_b32_e32 v0, 5, v8
	v_lshlrev_b32_e32 v1, 4, v8
	v_lshlrev_b32_e32 v9, 2, v8
	v_xor_b32_e32 v2, 0x4, v9
	v_xor_b32_e32 v3, 0x8, v9
	v_xor_b32_e32 v4, 0x10, v9
	v_xor_b32_e32 v5, 0x20, v9
	v_xor_b32_e32 v6, 0x40, v9
	v_xor_b32_e32 v7, 0x80, v9
	v_readlane_b32 s3, v240, 55
	v_readlane_b32 s6, v239, 10
	s_lshr_b32 s3, s3, 6
	s_lshl_b32 s3, s3, 2
	s_and_b32 s7, s78, 7
	s_lshl_b32 s7, s7, 10
	s_add_i32 s3, s3, s7
	s_lshr_b32 s7, s78, 3
	s_lshl_b32 s7, s7, 5
	s_add_i32 s3, s3, s7
	s_lshl_b32 s6, s6, 3
	s_cmpk_lt_i32 s3, 0x2000
	s_cbranch_scc0 .Lnorm2_end
.Lnorm2_loop:
	s_mov_b32 s8, s3
	s_add_i32 s9, s8, 1
	s_add_i32 s10, s9, 1
	s_add_i32 s11, s10, 1
	s_cmpk_lt_i32 s9, 0x2000
	s_cselect_b32 s9, s9, s3
	s_cmpk_lt_i32 s10, 0x2000
	s_cselect_b32 s10, s10, s3
	s_cmpk_lt_i32 s11, 0x2000
	s_cselect_b32 s11, s11, s3
	s_lshl_b32 s7, s8, 12
	s_add_u32 s4, s34, s7
	s_addc_u32 s5, s35, 0
	s_add_u32 s4, s4, 0x6900000
	s_addc_u32 s5, s5, 0
	global_load_dwordx4 v[16:19], v0, s[4:5]
	global_load_dwordx4 v[20:23], v0, s[4:5] offset:16
	global_load_dwordx4 v[24:27], v0, s[4:5] offset:2048
	global_load_dwordx4 v[28:31], v0, s[4:5] offset:2064
	s_lshl_b32 s7, s9, 12
	s_add_u32 s4, s34, s7
	s_addc_u32 s5, s35, 0
	s_add_u32 s4, s4, 0x6900000
	s_addc_u32 s5, s5, 0
	global_load_dwordx4 v[32:35], v0, s[4:5]
	global_load_dwordx4 v[36:39], v0, s[4:5] offset:16
	global_load_dwordx4 v[40:43], v0, s[4:5] offset:2048
	global_load_dwordx4 v[44:47], v0, s[4:5] offset:2064
	s_lshl_b32 s7, s10, 12
	s_add_u32 s4, s34, s7
	s_addc_u32 s5, s35, 0
	s_add_u32 s4, s4, 0x6900000
	s_addc_u32 s5, s5, 0
	global_load_dwordx4 v[48:51], v0, s[4:5]
	global_load_dwordx4 v[52:55], v0, s[4:5] offset:16
	global_load_dwordx4 v[56:59], v0, s[4:5] offset:2048
	global_load_dwordx4 v[60:63], v0, s[4:5] offset:2064
	s_lshl_b32 s7, s11, 12
	s_add_u32 s4, s34, s7
	s_addc_u32 s5, s35, 0
	s_add_u32 s4, s4, 0x6900000
	s_addc_u32 s5, s5, 0
	global_load_dwordx4 v[64:67], v0, s[4:5]
	global_load_dwordx4 v[68:71], v0, s[4:5] offset:16
	global_load_dwordx4 v[72:75], v0, s[4:5] offset:2048
	global_load_dwordx4 v[76:79], v0, s[4:5] offset:2064
	global_load_dwordx4 v[80:83], v0, s[18:19]
	global_load_dwordx4 v[84:87], v0, s[18:19] offset:16
	global_load_dwordx4 v[88:91], v0, s[18:19] offset:2048
	global_load_dwordx4 v[92:95], v0, s[18:19] offset:2064
	s_sub_i32 s7, s8, 0x1000
	s_lshr_b32 s7, s7, 11
	s_add_i32 s7, s7, 1
	s_cmpk_lt_i32 s8, 0x1000
	s_cselect_b32 s7, 0, s7
	s_mulk_i32 s7, 0x6000
	s_add_i32 s7, s7, 0x3000
	s_add_u32 s4, s14, s7
	s_addc_u32 s5, s15, 0
	global_load_dwordx4 v[112:115], v0, s[4:5]
	global_load_dwordx4 v[116:119], v0, s[4:5] offset:16
	global_load_dwordx4 v[120:123], v0, s[4:5] offset:2048
	global_load_dwordx4 v[124:127], v0, s[4:5] offset:2064
	s_add_u32 s4, s4, 0x1000
	s_addc_u32 s5, s5, 0
	global_load_dwordx4 v[96:99], v0, s[4:5]
	global_load_dwordx4 v[100:103], v0, s[4:5] offset:16
	global_load_dwordx4 v[104:107], v0, s[4:5] offset:2048
	global_load_dwordx4 v[108:111], v0, s[4:5] offset:2064
	s_sub_i32 s7, s9, 0x1000
	s_lshr_b32 s7, s7, 11
	s_add_i32 s7, s7, 1
	s_cmpk_lt_i32 s9, 0x1000
	s_cselect_b32 s7, 0, s7
	s_mulk_i32 s7, 0x6000
	s_add_i32 s7, s7, 0x3000
	s_add_u32 s4, s14, s7
	s_addc_u32 s5, s15, 0
	global_load_dwordx4 v[144:147], v0, s[4:5]
	global_load_dwordx4 v[148:151], v0, s[4:5] offset:16
	global_load_dwordx4 v[152:155], v0, s[4:5] offset:2048
	global_load_dwordx4 v[156:159], v0, s[4:5] offset:2064
	s_add_u32 s4, s4, 0x1000
	s_addc_u32 s5, s5, 0
	global_load_dwordx4 v[128:131], v0, s[4:5]
	global_load_dwordx4 v[132:135], v0, s[4:5] offset:16
	global_load_dwordx4 v[136:139], v0, s[4:5] offset:2048
	global_load_dwordx4 v[140:143], v0, s[4:5] offset:2064
	s_waitcnt vmcnt(32)
	v_mul_f32_e32 v160, v17, v17
	v_mul_f32_e32 v9, v19, v19
	v_fmac_f32_e32 v160, v16, v16
	v_fmac_f32_e32 v9, v18, v18
	v_add_f32_e32 v160, v160, v9
	v_mul_f32_e32 v8, v21, v21
	v_mul_f32_e32 v9, v23, v23
	v_fmac_f32_e32 v8, v20, v20
	v_fmac_f32_e32 v9, v22, v22
	v_add_f32_e32 v8, v8, v9
	v_add_f32_e32 v160, v160, v8
	v_mul_f32_e32 v8, v25, v25
	v_mul_f32_e32 v9, v27, v27
	v_fmac_f32_e32 v8, v24, v24
	v_fmac_f32_e32 v9, v26, v26
	v_add_f32_e32 v8, v8, v9
	v_add_f32_e32 v160, v160, v8
	v_mul_f32_e32 v8, v29, v29
	v_mul_f32_e32 v9, v31, v31
	v_fmac_f32_e32 v8, v28, v28
	v_fmac_f32_e32 v9, v30, v30
	v_add_f32_e32 v8, v8, v9
	v_add_f32_e32 v160, v160, v8
	s_waitcnt vmcnt(28)
	v_mul_f32_e32 v161, v33, v33
	v_mul_f32_e32 v9, v35, v35
	v_fmac_f32_e32 v161, v32, v32
	v_fmac_f32_e32 v9, v34, v34
	v_add_f32_e32 v161, v161, v9
	v_mul_f32_e32 v8, v37, v37
	v_mul_f32_e32 v9, v39, v39
	v_fmac_f32_e32 v8, v36, v36
	v_fmac_f32_e32 v9, v38, v38
	v_add_f32_e32 v8, v8, v9
	v_add_f32_e32 v161, v161, v8
	v_mul_f32_e32 v8, v41, v41
	v_mul_f32_e32 v9, v43, v43
	v_fmac_f32_e32 v8, v40, v40
	v_fmac_f32_e32 v9, v42, v42
	v_add_f32_e32 v8, v8, v9
	v_add_f32_e32 v161, v161, v8
	v_mul_f32_e32 v8, v45, v45
	v_mul_f32_e32 v9, v47, v47
	v_fmac_f32_e32 v8, v44, v44
	v_fmac_f32_e32 v9, v46, v46
	v_add_f32_e32 v8, v8, v9
	v_add_f32_e32 v161, v161, v8
	s_waitcnt vmcnt(24)
	v_mul_f32_e32 v162, v49, v49
	v_mul_f32_e32 v9, v51, v51
	v_fmac_f32_e32 v162, v48, v48
	v_fmac_f32_e32 v9, v50, v50
	v_add_f32_e32 v162, v162, v9
	v_mul_f32_e32 v8, v53, v53
	v_mul_f32_e32 v9, v55, v55
	v_fmac_f32_e32 v8, v52, v52
	v_fmac_f32_e32 v9, v54, v54
	v_add_f32_e32 v8, v8, v9
	v_add_f32_e32 v162, v162, v8
	v_mul_f32_e32 v8, v57, v57
	v_mul_f32_e32 v9, v59, v59
	v_fmac_f32_e32 v8, v56, v56
	v_fmac_f32_e32 v9, v58, v58
	v_add_f32_e32 v8, v8, v9
	v_add_f32_e32 v162, v162, v8
	v_mul_f32_e32 v8, v61, v61
	v_mul_f32_e32 v9, v63, v63
	v_fmac_f32_e32 v8, v60, v60
	v_fmac_f32_e32 v9, v62, v62
	v_add_f32_e32 v8, v8, v9
	v_add_f32_e32 v162, v162, v8
	s_waitcnt vmcnt(20)
	v_mul_f32_e32 v163, v65, v65
	v_mul_f32_e32 v9, v67, v67
	v_fmac_f32_e32 v163, v64, v64
	v_fmac_f32_e32 v9, v66, v66
	v_add_f32_e32 v163, v163, v9
	v_mul_f32_e32 v8, v69, v69
	v_mul_f32_e32 v9, v71, v71
	v_fmac_f32_e32 v8, v68, v68
	v_fmac_f32_e32 v9, v70, v70
	v_add_f32_e32 v8, v8, v9
	v_add_f32_e32 v163, v163, v8
	v_mul_f32_e32 v8, v73, v73
	v_mul_f32_e32 v9, v75, v75
	v_fmac_f32_e32 v8, v72, v72
	v_fmac_f32_e32 v9, v74, v74
	v_add_f32_e32 v8, v8, v9
	v_add_f32_e32 v163, v163, v8
	v_mul_f32_e32 v8, v77, v77
	v_mul_f32_e32 v9, v79, v79
	v_fmac_f32_e32 v8, v76, v76
	v_fmac_f32_e32 v9, v78, v78
	v_add_f32_e32 v8, v8, v9
	v_add_f32_e32 v163, v163, v8
	ds_bpermute_b32 v8, v2, v160
	ds_bpermute_b32 v9, v2, v161
	ds_bpermute_b32 v10, v2, v162
	ds_bpermute_b32 v11, v2, v163
	s_waitcnt lgkmcnt(3)
	v_add_f32_e32 v160, v160, v8
	s_waitcnt lgkmcnt(2)
	v_add_f32_e32 v161, v161, v9
	s_waitcnt lgkmcnt(1)
	v_add_f32_e32 v162, v162, v10
	s_waitcnt lgkmcnt(0)
	v_add_f32_e32 v163, v163, v11
	ds_bpermute_b32 v8, v3, v160
	ds_bpermute_b32 v9, v3, v161
	ds_bpermute_b32 v10, v3, v162
	ds_bpermute_b32 v11, v3, v163
	s_waitcnt lgkmcnt(3)
	v_add_f32_e32 v160, v160, v8
	s_waitcnt lgkmcnt(2)
	v_add_f32_e32 v161, v161, v9
	s_waitcnt lgkmcnt(1)
	v_add_f32_e32 v162, v162, v10
	s_waitcnt lgkmcnt(0)
	v_add_f32_e32 v163, v163, v11
	ds_bpermute_b32 v8, v4, v160
	ds_bpermute_b32 v9, v4, v161
	ds_bpermute_b32 v10, v4, v162
	ds_bpermute_b32 v11, v4, v163
	s_waitcnt lgkmcnt(3)
	v_add_f32_e32 v160, v160, v8
	s_waitcnt lgkmcnt(2)
	v_add_f32_e32 v161, v161, v9
	s_waitcnt lgkmcnt(1)
	v_add_f32_e32 v162, v162, v10
	s_waitcnt lgkmcnt(0)
	v_add_f32_e32 v163, v163, v11
	ds_bpermute_b32 v8, v5, v160
	ds_bpermute_b32 v9, v5, v161
	ds_bpermute_b32 v10, v5, v162
	ds_bpermute_b32 v11, v5, v163
	s_waitcnt lgkmcnt(3)
	v_add_f32_e32 v160, v160, v8
	s_waitcnt lgkmcnt(2)
	v_add_f32_e32 v161, v161, v9
	s_waitcnt lgkmcnt(1)
	v_add_f32_e32 v162, v162, v10
	s_waitcnt lgkmcnt(0)
	v_add_f32_e32 v163, v163, v11
	ds_bpermute_b32 v8, v6, v160
	ds_bpermute_b32 v9, v6, v161
	ds_bpermute_b32 v10, v6, v162
	ds_bpermute_b32 v11, v6, v163
	s_waitcnt lgkmcnt(3)
	v_add_f32_e32 v160, v160, v8
	s_waitcnt lgkmcnt(2)
	v_add_f32_e32 v161, v161, v9
	s_waitcnt lgkmcnt(1)
	v_add_f32_e32 v162, v162, v10
	s_waitcnt lgkmcnt(0)
	v_add_f32_e32 v163, v163, v11
	ds_bpermute_b32 v8, v7, v160
	ds_bpermute_b32 v9, v7, v161
	ds_bpermute_b32 v10, v7, v162
	ds_bpermute_b32 v11, v7, v163
	s_waitcnt lgkmcnt(3)
	v_add_f32_e32 v160, v160, v8
	s_waitcnt lgkmcnt(2)
	v_add_f32_e32 v161, v161, v9
	s_waitcnt lgkmcnt(1)
	v_add_f32_e32 v162, v162, v10
	s_waitcnt lgkmcnt(0)
	v_add_f32_e32 v163, v163, v11
	s_mov_b32 s7, 0xf800000
	v_fmamk_f32 v160, v160, 0x3a800000, v190
	v_mul_f32_e32 v8, 0x4f800000, v160
	v_cmp_gt_f32_e32 vcc, s7, v160
	s_nop 1
	v_cndmask_b32_e32 v160, v160, v8, vcc
	v_sqrt_f32_e32 v8, v160
	s_nop 0
	v_add_u32_e32 v9, -1, v8
	v_fma_f32 v10, -v9, v8, v160
	v_cmp_ge_f32_e64 s[4:5], 0, v10
	v_add_u32_e32 v10, 1, v8
	s_nop 0
	v_cndmask_b32_e64 v9, v8, v9, s[4:5]
	v_fma_f32 v8, -v10, v8, v160
	v_cmp_lt_f32_e64 s[4:5], 0, v8
	s_nop 1
	v_cndmask_b32_e64 v8, v9, v10, s[4:5]
	v_mul_f32_e32 v9, 0x37800000, v8
	v_cndmask_b32_e32 v8, v8, v9, vcc
	v_cmp_class_f32_e32 vcc, v160, v191
	s_nop 1
	v_cndmask_b32_e32 v160, v8, v160, vcc
	v_div_scale_f32 v8, s[4:5], v160, v160, 1.0
	v_rcp_f32_e32 v9, v8
	s_nop 0
	v_fma_f32 v10, -v8, v9, 1.0
	v_fmac_f32_e32 v9, v10, v9
	v_div_scale_f32 v10, vcc, 1.0, v160, 1.0
	v_mul_f32_e32 v11, v10, v9
	v_fma_f32 v12, -v8, v11, v10
	v_fmac_f32_e32 v11, v12, v9
	v_fma_f32 v8, -v8, v11, v10
	v_div_fmas_f32 v8, v8, v9, v11
	v_div_fixup_f32 v160, v8, v160, 1.0
	s_mov_b32 s7, 0xf800000
	v_fmamk_f32 v161, v161, 0x3a800000, v190
	v_mul_f32_e32 v8, 0x4f800000, v161
	v_cmp_gt_f32_e32 vcc, s7, v161
	s_nop 1
	v_cndmask_b32_e32 v161, v161, v8, vcc
	v_sqrt_f32_e32 v8, v161
	s_nop 0
	v_add_u32_e32 v9, -1, v8
	v_fma_f32 v10, -v9, v8, v161
	v_cmp_ge_f32_e64 s[4:5], 0, v10
	v_add_u32_e32 v10, 1, v8
	s_nop 0
	v_cndmask_b32_e64 v9, v8, v9, s[4:5]
	v_fma_f32 v8, -v10, v8, v161
	v_cmp_lt_f32_e64 s[4:5], 0, v8
	s_nop 1
	v_cndmask_b32_e64 v8, v9, v10, s[4:5]
	v_mul_f32_e32 v9, 0x37800000, v8
	v_cndmask_b32_e32 v8, v8, v9, vcc
	v_cmp_class_f32_e32 vcc, v161, v191
	s_nop 1
	v_cndmask_b32_e32 v161, v8, v161, vcc
	v_div_scale_f32 v8, s[4:5], v161, v161, 1.0
	v_rcp_f32_e32 v9, v8
	s_nop 0
	v_fma_f32 v10, -v8, v9, 1.0
	v_fmac_f32_e32 v9, v10, v9
	v_div_scale_f32 v10, vcc, 1.0, v161, 1.0
	v_mul_f32_e32 v11, v10, v9
	v_fma_f32 v12, -v8, v11, v10
	v_fmac_f32_e32 v11, v12, v9
	v_fma_f32 v8, -v8, v11, v10
	v_div_fmas_f32 v8, v8, v9, v11
	v_div_fixup_f32 v161, v8, v161, 1.0
	s_mov_b32 s7, 0xf800000
	v_fmamk_f32 v162, v162, 0x3a800000, v190
	v_mul_f32_e32 v8, 0x4f800000, v162
	v_cmp_gt_f32_e32 vcc, s7, v162
	s_nop 1
	v_cndmask_b32_e32 v162, v162, v8, vcc
	v_sqrt_f32_e32 v8, v162
	s_nop 0
	v_add_u32_e32 v9, -1, v8
	v_fma_f32 v10, -v9, v8, v162
	v_cmp_ge_f32_e64 s[4:5], 0, v10
	v_add_u32_e32 v10, 1, v8
	s_nop 0
	v_cndmask_b32_e64 v9, v8, v9, s[4:5]
	v_fma_f32 v8, -v10, v8, v162
	v_cmp_lt_f32_e64 s[4:5], 0, v8
	s_nop 1
	v_cndmask_b32_e64 v8, v9, v10, s[4:5]
	v_mul_f32_e32 v9, 0x37800000, v8
	v_cndmask_b32_e32 v8, v8, v9, vcc
	v_cmp_class_f32_e32 vcc, v162, v191
	s_nop 1
	v_cndmask_b32_e32 v162, v8, v162, vcc
	v_div_scale_f32 v8, s[4:5], v162, v162, 1.0
	v_rcp_f32_e32 v9, v8
	s_nop 0
	v_fma_f32 v10, -v8, v9, 1.0
	v_fmac_f32_e32 v9, v10, v9
	v_div_scale_f32 v10, vcc, 1.0, v162, 1.0
	v_mul_f32_e32 v11, v10, v9
	v_fma_f32 v12, -v8, v11, v10
	v_fmac_f32_e32 v11, v12, v9
	v_fma_f32 v8, -v8, v11, v10
	v_div_fmas_f32 v8, v8, v9, v11
	v_div_fixup_f32 v162, v8, v162, 1.0
	s_mov_b32 s7, 0xf800000
	v_fmamk_f32 v163, v163, 0x3a800000, v190
	v_mul_f32_e32 v8, 0x4f800000, v163
	v_cmp_gt_f32_e32 vcc, s7, v163
	s_nop 1
	v_cndmask_b32_e32 v163, v163, v8, vcc
	v_sqrt_f32_e32 v8, v163
	s_nop 0
	v_add_u32_e32 v9, -1, v8
	v_fma_f32 v10, -v9, v8, v163
	v_cmp_ge_f32_e64 s[4:5], 0, v10
	v_add_u32_e32 v10, 1, v8
	s_nop 0
	v_cndmask_b32_e64 v9, v8, v9, s[4:5]
	v_fma_f32 v8, -v10, v8, v163
	v_cmp_lt_f32_e64 s[4:5], 0, v8
	s_nop 1
	v_cndmask_b32_e64 v8, v9, v10, s[4:5]
	v_mul_f32_e32 v9, 0x37800000, v8
	v_cndmask_b32_e32 v8, v8, v9, vcc
	v_cmp_class_f32_e32 vcc, v163, v191
	s_nop 1
	v_cndmask_b32_e32 v163, v8, v163, vcc
	v_div_scale_f32 v8, s[4:5], v163, v163, 1.0
	v_rcp_f32_e32 v9, v8
	s_nop 0
	v_fma_f32 v10, -v8, v9, 1.0
	v_fmac_f32_e32 v9, v10, v9
	v_div_scale_f32 v10, vcc, 1.0, v163, 1.0
	v_mul_f32_e32 v11, v10, v9
	v_fma_f32 v12, -v8, v11, v10
	v_fmac_f32_e32 v11, v12, v9
	v_fma_f32 v8, -v8, v11, v10
	v_div_fmas_f32 v8, v8, v9, v11
	v_div_fixup_f32 v163, v8, v163, 1.0
	s_waitcnt vmcnt(8)
	s_lshl_b32 s7, s8, 11
	s_add_u32 s4, s34, s7
	s_addc_u32 s5, s35, 0
	s_add_u32 s4, s4, 0x8900000
	s_addc_u32 s5, s5, 0
	v_mul_f32_e32 v19, v19, v160
	v_mul_f32_e32 v19, v83, v19
	v_mul_f32_e32 v18, v18, v160
	v_mul_f32_e32 v18, v82, v18
	v_mul_f32_e32 v17, v17, v160
	v_mul_f32_e32 v17, v81, v17
	v_mul_f32_e32 v16, v16, v160
	v_mul_f32_e32 v16, v80, v16
	v_add_f32_e32 v11, 1.0, v99
	v_fma_f32 v19, v11, v19, v115
	v_add_f32_e32 v10, 1.0, v98
	v_fma_f32 v18, v10, v18, v114
	v_add_f32_e32 v9, 1.0, v97
	v_fma_f32 v17, v9, v17, v113
	v_add_f32_e32 v8, 1.0, v96
	v_fma_f32 v16, v8, v16, v112
	v_mul_f32_e32 v23, v23, v160
	v_mul_f32_e32 v23, v87, v23
	v_mul_f32_e32 v22, v22, v160
	v_mul_f32_e32 v22, v86, v22
	v_mul_f32_e32 v21, v21, v160
	v_mul_f32_e32 v21, v85, v21
	v_mul_f32_e32 v20, v20, v160
	v_mul_f32_e32 v20, v84, v20
	v_add_f32_e32 v11, 1.0, v103
	v_fma_f32 v23, v11, v23, v119
	v_add_f32_e32 v10, 1.0, v102
	v_fma_f32 v22, v10, v22, v118
	v_add_f32_e32 v9, 1.0, v101
	v_fma_f32 v21, v9, v21, v117
	v_add_f32_e32 v8, 1.0, v100
	v_fma_f32 v20, v8, v20, v116
	v_cvt_pk_bf16_f32 v16, v16, v17
	v_cvt_pk_bf16_f32 v17, v18, v19
	v_cvt_pk_bf16_f32 v18, v20, v21
	v_cvt_pk_bf16_f32 v19, v22, v23
	global_store_dwordx4 v1, v[16:19], s[4:5]
	v_mul_f32_e32 v27, v27, v160
	v_mul_f32_e32 v27, v91, v27
	v_mul_f32_e32 v26, v26, v160
	v_mul_f32_e32 v26, v90, v26
	v_mul_f32_e32 v25, v25, v160
	v_mul_f32_e32 v25, v89, v25
	v_mul_f32_e32 v24, v24, v160
	v_mul_f32_e32 v24, v88, v24
	v_add_f32_e32 v11, 1.0, v107
	v_fma_f32 v27, v11, v27, v123
	v_add_f32_e32 v10, 1.0, v106
	v_fma_f32 v26, v10, v26, v122
	v_add_f32_e32 v9, 1.0, v105
	v_fma_f32 v25, v9, v25, v121
	v_add_f32_e32 v8, 1.0, v104
	v_fma_f32 v24, v8, v24, v120
	v_mul_f32_e32 v31, v31, v160
	v_mul_f32_e32 v31, v95, v31
	v_mul_f32_e32 v30, v30, v160
	v_mul_f32_e32 v30, v94, v30
	v_mul_f32_e32 v29, v29, v160
	v_mul_f32_e32 v29, v93, v29
	v_mul_f32_e32 v28, v28, v160
	v_mul_f32_e32 v28, v92, v28
	v_add_f32_e32 v11, 1.0, v111
	v_fma_f32 v31, v11, v31, v127
	v_add_f32_e32 v10, 1.0, v110
	v_fma_f32 v30, v10, v30, v126
	v_add_f32_e32 v9, 1.0, v109
	v_fma_f32 v29, v9, v29, v125
	v_add_f32_e32 v8, 1.0, v108
	v_fma_f32 v28, v8, v28, v124
	v_cvt_pk_bf16_f32 v24, v24, v25
	v_cvt_pk_bf16_f32 v25, v26, v27
	v_cvt_pk_bf16_f32 v26, v28, v29
	v_cvt_pk_bf16_f32 v27, v30, v31
	global_store_dwordx4 v1, v[24:27], s[4:5] offset:1024
	s_sub_i32 s7, s10, 0x1000
	s_lshr_b32 s7, s7, 11
	s_add_i32 s7, s7, 1
	s_cmpk_lt_i32 s10, 0x1000
	s_cselect_b32 s7, 0, s7
	s_mulk_i32 s7, 0x6000
	s_add_i32 s7, s7, 0x3000
	s_add_u32 s4, s14, s7
	s_addc_u32 s5, s15, 0
	global_load_dwordx4 v[112:115], v0, s[4:5]
	global_load_dwordx4 v[116:119], v0, s[4:5] offset:16
	global_load_dwordx4 v[120:123], v0, s[4:5] offset:2048
	global_load_dwordx4 v[124:127], v0, s[4:5] offset:2064
	s_add_u32 s4, s4, 0x1000
	s_addc_u32 s5, s5, 0
	global_load_dwordx4 v[96:99], v0, s[4:5]
	global_load_dwordx4 v[100:103], v0, s[4:5] offset:16
	global_load_dwordx4 v[104:107], v0, s[4:5] offset:2048
	global_load_dwordx4 v[108:111], v0, s[4:5] offset:2064
	s_waitcnt vmcnt(10)
	s_lshl_b32 s7, s9, 11
	s_add_u32 s4, s34, s7
	s_addc_u32 s5, s35, 0
	s_add_u32 s4, s4, 0x8900000
	s_addc_u32 s5, s5, 0
	v_mul_f32_e32 v35, v35, v161
	v_mul_f32_e32 v35, v83, v35
	v_mul_f32_e32 v34, v34, v161
	v_mul_f32_e32 v34, v82, v34
	v_mul_f32_e32 v33, v33, v161
	v_mul_f32_e32 v33, v81, v33
	v_mul_f32_e32 v32, v32, v161
	v_mul_f32_e32 v32, v80, v32
	v_add_f32_e32 v11, 1.0, v131
	v_fma_f32 v35, v11, v35, v147
	v_add_f32_e32 v10, 1.0, v130
	v_fma_f32 v34, v10, v34, v146
	v_add_f32_e32 v9, 1.0, v129
	v_fma_f32 v33, v9, v33, v145
	v_add_f32_e32 v8, 1.0, v128
	v_fma_f32 v32, v8, v32, v144
	v_mul_f32_e32 v39, v39, v161
	v_mul_f32_e32 v39, v87, v39
	v_mul_f32_e32 v38, v38, v161
	v_mul_f32_e32 v38, v86, v38
	v_mul_f32_e32 v37, v37, v161
	v_mul_f32_e32 v37, v85, v37
	v_mul_f32_e32 v36, v36, v161
	v_mul_f32_e32 v36, v84, v36
	v_add_f32_e32 v11, 1.0, v135
	v_fma_f32 v39, v11, v39, v151
	v_add_f32_e32 v10, 1.0, v134
	v_fma_f32 v38, v10, v38, v150
	v_add_f32_e32 v9, 1.0, v133
	v_fma_f32 v37, v9, v37, v149
	v_add_f32_e32 v8, 1.0, v132
	v_fma_f32 v36, v8, v36, v148
	v_cvt_pk_bf16_f32 v32, v32, v33
	v_cvt_pk_bf16_f32 v33, v34, v35
	v_cvt_pk_bf16_f32 v34, v36, v37
	v_cvt_pk_bf16_f32 v35, v38, v39
	global_store_dwordx4 v1, v[32:35], s[4:5]
	v_mul_f32_e32 v43, v43, v161
	v_mul_f32_e32 v43, v91, v43
	v_mul_f32_e32 v42, v42, v161
	v_mul_f32_e32 v42, v90, v42
	v_mul_f32_e32 v41, v41, v161
	v_mul_f32_e32 v41, v89, v41
	v_mul_f32_e32 v40, v40, v161
	v_mul_f32_e32 v40, v88, v40
	v_add_f32_e32 v11, 1.0, v139
	v_fma_f32 v43, v11, v43, v155
	v_add_f32_e32 v10, 1.0, v138
	v_fma_f32 v42, v10, v42, v154
	v_add_f32_e32 v9, 1.0, v137
	v_fma_f32 v41, v9, v41, v153
	v_add_f32_e32 v8, 1.0, v136
	v_fma_f32 v40, v8, v40, v152
	v_mul_f32_e32 v47, v47, v161
	v_mul_f32_e32 v47, v95, v47
	v_mul_f32_e32 v46, v46, v161
	v_mul_f32_e32 v46, v94, v46
	v_mul_f32_e32 v45, v45, v161
	v_mul_f32_e32 v45, v93, v45
	v_mul_f32_e32 v44, v44, v161
	v_mul_f32_e32 v44, v92, v44
	v_add_f32_e32 v11, 1.0, v143
	v_fma_f32 v47, v11, v47, v159
	v_add_f32_e32 v10, 1.0, v142
	v_fma_f32 v46, v10, v46, v158
	v_add_f32_e32 v9, 1.0, v141
	v_fma_f32 v45, v9, v45, v157
	v_add_f32_e32 v8, 1.0, v140
	v_fma_f32 v44, v8, v44, v156
	v_cvt_pk_bf16_f32 v40, v40, v41
	v_cvt_pk_bf16_f32 v41, v42, v43
	v_cvt_pk_bf16_f32 v42, v44, v45
	v_cvt_pk_bf16_f32 v43, v46, v47
	global_store_dwordx4 v1, v[40:43], s[4:5] offset:1024
	s_sub_i32 s7, s11, 0x1000
	s_lshr_b32 s7, s7, 11
	s_add_i32 s7, s7, 1
	s_cmpk_lt_i32 s11, 0x1000
	s_cselect_b32 s7, 0, s7
	s_mulk_i32 s7, 0x6000
	s_add_i32 s7, s7, 0x3000
	s_add_u32 s4, s14, s7
	s_addc_u32 s5, s15, 0
	global_load_dwordx4 v[144:147], v0, s[4:5]
	global_load_dwordx4 v[148:151], v0, s[4:5] offset:16
	global_load_dwordx4 v[152:155], v0, s[4:5] offset:2048
	global_load_dwordx4 v[156:159], v0, s[4:5] offset:2064
	s_add_u32 s4, s4, 0x1000
	s_addc_u32 s5, s5, 0
	global_load_dwordx4 v[128:131], v0, s[4:5]
	global_load_dwordx4 v[132:135], v0, s[4:5] offset:16
	global_load_dwordx4 v[136:139], v0, s[4:5] offset:2048
	global_load_dwordx4 v[140:143], v0, s[4:5] offset:2064
	s_waitcnt vmcnt(10)
	s_lshl_b32 s7, s10, 11
	s_add_u32 s4, s34, s7
	s_addc_u32 s5, s35, 0
	s_add_u32 s4, s4, 0x8900000
	s_addc_u32 s5, s5, 0
	v_mul_f32_e32 v51, v51, v162
	v_mul_f32_e32 v51, v83, v51
	v_mul_f32_e32 v50, v50, v162
	v_mul_f32_e32 v50, v82, v50
	v_mul_f32_e32 v49, v49, v162
	v_mul_f32_e32 v49, v81, v49
	v_mul_f32_e32 v48, v48, v162
	v_mul_f32_e32 v48, v80, v48
	v_add_f32_e32 v11, 1.0, v99
	v_fma_f32 v51, v11, v51, v115
	v_add_f32_e32 v10, 1.0, v98
	v_fma_f32 v50, v10, v50, v114
	v_add_f32_e32 v9, 1.0, v97
	v_fma_f32 v49, v9, v49, v113
	v_add_f32_e32 v8, 1.0, v96
	v_fma_f32 v48, v8, v48, v112
	v_mul_f32_e32 v55, v55, v162
	v_mul_f32_e32 v55, v87, v55
	v_mul_f32_e32 v54, v54, v162
	v_mul_f32_e32 v54, v86, v54
	v_mul_f32_e32 v53, v53, v162
	v_mul_f32_e32 v53, v85, v53
	v_mul_f32_e32 v52, v52, v162
	v_mul_f32_e32 v52, v84, v52
	v_add_f32_e32 v11, 1.0, v103
	v_fma_f32 v55, v11, v55, v119
	v_add_f32_e32 v10, 1.0, v102
	v_fma_f32 v54, v10, v54, v118
	v_add_f32_e32 v9, 1.0, v101
	v_fma_f32 v53, v9, v53, v117
	v_add_f32_e32 v8, 1.0, v100
	v_fma_f32 v52, v8, v52, v116
	v_cvt_pk_bf16_f32 v48, v48, v49
	v_cvt_pk_bf16_f32 v49, v50, v51
	v_cvt_pk_bf16_f32 v50, v52, v53
	v_cvt_pk_bf16_f32 v51, v54, v55
	global_store_dwordx4 v1, v[48:51], s[4:5]
	v_mul_f32_e32 v59, v59, v162
	v_mul_f32_e32 v59, v91, v59
	v_mul_f32_e32 v58, v58, v162
	v_mul_f32_e32 v58, v90, v58
	v_mul_f32_e32 v57, v57, v162
	v_mul_f32_e32 v57, v89, v57
	v_mul_f32_e32 v56, v56, v162
	v_mul_f32_e32 v56, v88, v56
	v_add_f32_e32 v11, 1.0, v107
	v_fma_f32 v59, v11, v59, v123
	v_add_f32_e32 v10, 1.0, v106
	v_fma_f32 v58, v10, v58, v122
	v_add_f32_e32 v9, 1.0, v105
	v_fma_f32 v57, v9, v57, v121
	v_add_f32_e32 v8, 1.0, v104
	v_fma_f32 v56, v8, v56, v120
	v_mul_f32_e32 v63, v63, v162
	v_mul_f32_e32 v63, v95, v63
	v_mul_f32_e32 v62, v62, v162
	v_mul_f32_e32 v62, v94, v62
	v_mul_f32_e32 v61, v61, v162
	v_mul_f32_e32 v61, v93, v61
	v_mul_f32_e32 v60, v60, v162
	v_mul_f32_e32 v60, v92, v60
	v_add_f32_e32 v11, 1.0, v111
	v_fma_f32 v63, v11, v63, v127
	v_add_f32_e32 v10, 1.0, v110
	v_fma_f32 v62, v10, v62, v126
	v_add_f32_e32 v9, 1.0, v109
	v_fma_f32 v61, v9, v61, v125
	v_add_f32_e32 v8, 1.0, v108
	v_fma_f32 v60, v8, v60, v124
	v_cvt_pk_bf16_f32 v56, v56, v57
	v_cvt_pk_bf16_f32 v57, v58, v59
	v_cvt_pk_bf16_f32 v58, v60, v61
	v_cvt_pk_bf16_f32 v59, v62, v63
	global_store_dwordx4 v1, v[56:59], s[4:5] offset:1024
	s_waitcnt vmcnt(2)
	s_lshl_b32 s7, s11, 11
	s_add_u32 s4, s34, s7
	s_addc_u32 s5, s35, 0
	s_add_u32 s4, s4, 0x8900000
	s_addc_u32 s5, s5, 0
	v_mul_f32_e32 v67, v67, v163
	v_mul_f32_e32 v67, v83, v67
	v_mul_f32_e32 v66, v66, v163
	v_mul_f32_e32 v66, v82, v66
	v_mul_f32_e32 v65, v65, v163
	v_mul_f32_e32 v65, v81, v65
	v_mul_f32_e32 v64, v64, v163
	v_mul_f32_e32 v64, v80, v64
	v_add_f32_e32 v11, 1.0, v131
	v_fma_f32 v67, v11, v67, v147
	v_add_f32_e32 v10, 1.0, v130
	v_fma_f32 v66, v10, v66, v146
	v_add_f32_e32 v9, 1.0, v129
	v_fma_f32 v65, v9, v65, v145
	v_add_f32_e32 v8, 1.0, v128
	v_fma_f32 v64, v8, v64, v144
	v_mul_f32_e32 v71, v71, v163
	v_mul_f32_e32 v71, v87, v71
	v_mul_f32_e32 v70, v70, v163
	v_mul_f32_e32 v70, v86, v70
	v_mul_f32_e32 v69, v69, v163
	v_mul_f32_e32 v69, v85, v69
	v_mul_f32_e32 v68, v68, v163
	v_mul_f32_e32 v68, v84, v68
	v_add_f32_e32 v11, 1.0, v135
	v_fma_f32 v71, v11, v71, v151
	v_add_f32_e32 v10, 1.0, v134
	v_fma_f32 v70, v10, v70, v150
	v_add_f32_e32 v9, 1.0, v133
	v_fma_f32 v69, v9, v69, v149
	v_add_f32_e32 v8, 1.0, v132
	v_fma_f32 v68, v8, v68, v148
	v_cvt_pk_bf16_f32 v64, v64, v65
	v_cvt_pk_bf16_f32 v65, v66, v67
	v_cvt_pk_bf16_f32 v66, v68, v69
	v_cvt_pk_bf16_f32 v67, v70, v71
	global_store_dwordx4 v1, v[64:67], s[4:5]
	v_mul_f32_e32 v75, v75, v163
	v_mul_f32_e32 v75, v91, v75
	v_mul_f32_e32 v74, v74, v163
	v_mul_f32_e32 v74, v90, v74
	v_mul_f32_e32 v73, v73, v163
	v_mul_f32_e32 v73, v89, v73
	v_mul_f32_e32 v72, v72, v163
	v_mul_f32_e32 v72, v88, v72
	v_add_f32_e32 v11, 1.0, v139
	v_fma_f32 v75, v11, v75, v155
	v_add_f32_e32 v10, 1.0, v138
	v_fma_f32 v74, v10, v74, v154
	v_add_f32_e32 v9, 1.0, v137
	v_fma_f32 v73, v9, v73, v153
	v_add_f32_e32 v8, 1.0, v136
	v_fma_f32 v72, v8, v72, v152
	v_mul_f32_e32 v79, v79, v163
	v_mul_f32_e32 v79, v95, v79
	v_mul_f32_e32 v78, v78, v163
	v_mul_f32_e32 v78, v94, v78
	v_mul_f32_e32 v77, v77, v163
	v_mul_f32_e32 v77, v93, v77
	v_mul_f32_e32 v76, v76, v163
	v_mul_f32_e32 v76, v92, v76
	v_add_f32_e32 v11, 1.0, v143
	v_fma_f32 v79, v11, v79, v159
	v_add_f32_e32 v10, 1.0, v142
	v_fma_f32 v78, v10, v78, v158
	v_add_f32_e32 v9, 1.0, v141
	v_fma_f32 v77, v9, v77, v157
	v_add_f32_e32 v8, 1.0, v140
	v_fma_f32 v76, v8, v76, v156
	v_cvt_pk_bf16_f32 v72, v72, v73
	v_cvt_pk_bf16_f32 v73, v74, v75
	v_cvt_pk_bf16_f32 v74, v76, v77
	v_cvt_pk_bf16_f32 v75, v78, v79
	global_store_dwordx4 v1, v[72:75], s[4:5] offset:1024
	s_lshl_b32 s7, s6, 2
	s_add_i32 s3, s3, s7
	s_cmpk_lt_i32 s3, 0x2000
	s_cbranch_scc1 .Lnorm2_loop

.LBB0_100:
	v_ashrrev_i32_e32 v1, 31, v210
	v_lshrrev_b32_e32 v1, 26, v1
	v_add_u32_e32 v1, v210, v1
	v_ashrrev_i32_e32 v88, 6, v1
	v_bfe_i32 v1, v210, 27, 1
	v_lshlrev_b32_e32 v0, 4, v210
	v_lshrrev_b32_e32 v1, 22, v1
	v_add_u32_e32 v1, v0, v1
	v_and_b32_e32 v1, 0xfffffc00, v1
	v_sub_u32_e32 v1, v0, v1
	v_lshrrev_b32_e32 v2, 4, v1
	v_bitop3_b32 v1, v2, v1, 32 bitop3:0x6c
	v_ashrrev_i32_e32 v3, 31, v1
	v_lshrrev_b32_e32 v3, 26, v3
	v_add_u32_e32 v3, v1, v3
	v_ashrrev_i32_e32 v89, 6, v3
	v_and_b32_e32 v3, 0xc0, v3
	v_sub_u32_e32 v1, v1, v3
	v_lshlrev_b32_e32 v2, 3, v88
	v_lshlrev_b32_e32 v4, 5, v88
	v_ashrrev_i16_sdwa v1, v198, sext(v1) dst_sel:DWORD dst_unused:UNUSED_PAD src0_sel:DWORD src1_sel:BYTE_0
	v_and_b32_e32 v2, 0x1ffff0, v2
	v_and_b32_e32 v4, 32, v4
	v_bfe_i32 v90, v1, 0, 16
	v_add_u32_e32 v1, v4, v90
	v_add_lshl_u32 v2, v89, v2, 11
	v_add_u32_e32 v0, 0x2000, v0
	v_lshl_add_u32 v164, v1, 1, v2
	v_ashrrev_i32_e32 v1, 31, v0
	v_lshrrev_b32_e32 v1, 22, v1
	v_add_u32_e32 v1, v0, v1
	v_ashrrev_i32_e32 v91, 10, v1
	v_mul_i32_i24_e32 v1, 0x400, v91
	v_sub_u32_e32 v0, v0, v1
	v_lshrrev_b32_e32 v1, 4, v0
	v_bitop3_b32 v0, v1, v0, 32 bitop3:0x6c
	v_ashrrev_i32_e32 v2, 31, v0
	v_readlane_b32 s4, v239, 47
	v_lshrrev_b32_e32 v2, 26, v2
	s_add_u32 s81, s34, 0x9900000
	v_readlane_b32 s5, v239, 48
	v_add_u32_e32 v2, v0, v2
	s_addc_u32 s88, s35, 0
	s_ashr_i32 s5, s4, 31
	v_ashrrev_i32_e32 v92, 6, v2
	v_and_b32_e32 v2, 0xc0, v2
	v_writelane_b32 v239, s4, 47
	v_sub_u32_e32 v0, v0, v2
	v_lshlrev_b32_e32 v1, 3, v91
	v_writelane_b32 v239, s5, 48
	v_lshlrev_b32_e32 v3, 5, v91
	v_ashrrev_i16_sdwa v0, v198, sext(v0) dst_sel:DWORD dst_unused:UNUSED_PAD src0_sel:DWORD src1_sel:BYTE_0
	v_and_b32_e32 v1, 0x1ffff0, v1
	v_and_b32_e32 v3, 32, v3
	v_bfe_i32 v93, v0, 0, 16
	v_readlane_b32 s8, v239, 49
	s_add_u32 s6, s34, 0x6900000
	v_add_u32_e32 v0, v3, v93
	v_add_lshl_u32 v1, v92, v1, 11
	v_readlane_b32 s9, v239, 50
	s_addc_u32 s7, s35, 0
	v_lshl_add_u32 v152, v0, 1, v1
	v_and_b32_e32 v94, 15, v211
	v_and_b32_e32 v95, 48, v211
	s_mov_b64 s[4:5], -1
	s_and_b64 vcc, exec, s[8:9]
	s_cbranch_vccz .LBB0_132
	s_cmpk_gt_i32 s78, 0xff
	v_readfirstlane_b32 s15, v210
	s_cbranch_scc1 .LBB0_131
	s_and_b32 s98, s78, 6
	s_lshr_b32 s99, s78, 7
	s_add_i32 s98, s98, s99
	s_bfe_u32 s99, s78, 0x20005
	s_lshl_b32 s99, s99, 6
	s_add_i32 s98, s98, s99
	s_and_b32 s99, s78, 1
	s_lshl_b32 s99, s99, 5
	s_add_i32 s98, s98, s99
	s_and_b32 s99, s78, 0x18
	s_add_i32 s98, s98, s99
	s_ashr_i32 s3, s98, 31
	s_lshr_b32 s3, s3, 29
	s_add_i32 s3, s98, s3
	s_and_b32 s4, s3, -8
	s_sub_i32 s8, s98, s4
	v_readlane_b32 s56, v240, 62
	s_cmp_gt_i32 s8, -1
	s_mov_b64 s[4:5], -1
	v_readlane_b32 s57, v240, 63
	s_cbranch_scc0 .LBB0_104
	s_lshl_b32 s9, s8, 5
	s_mov_b64 s[4:5], 0

.LBB0_132:
	s_andn2_b64 vcc, exec, s[4:5]
	s_cbranch_vccnz .LBB0_159
	s_cmpk_gt_i32 s78, 0xff
	v_readfirstlane_b32 s8, v210
	s_cbranch_scc1 .LBB0_159
	s_and_b32 s98, s78, 6
	s_lshr_b32 s99, s78, 7
	s_add_i32 s98, s98, s99
	s_bfe_u32 s99, s78, 0x20005
	s_lshl_b32 s99, s99, 6
	s_add_i32 s98, s98, s99
	s_and_b32 s99, s78, 1
	s_lshl_b32 s99, s99, 5
	s_add_i32 s98, s98, s99
	s_and_b32 s99, s78, 0x18
	s_add_i32 s98, s98, s99
	s_ashr_i32 s3, s98, 31
	s_lshr_b32 s3, s3, 29
	s_add_i32 s10, s98, s3
	s_and_b32 s3, s10, -8
	s_sub_i32 s3, s98, s3
	s_cmp_gt_i32 s3, -1
	s_mov_b64 s[4:5], -1
	s_cbranch_scc0 .LBB0_136
	s_lshl_b32 s11, s3, 5
	s_mov_b64 s[4:5], 0

.LBB0_265:
	s_and_b64 vcc, exec, s[84:85]
	s_cbranch_vccz .LBB0_293
	s_cmpk_gt_i32 s78, 0xff
	v_readfirstlane_b32 s8, v210
	s_cbranch_scc1 .LBB0_292
	s_and_b32 s98, s78, 6
	s_lshr_b32 s99, s78, 7
	s_add_i32 s98, s98, s99
	s_bfe_u32 s99, s78, 0x20005
	s_lshl_b32 s99, s99, 6
	s_add_i32 s98, s98, s99
	s_and_b32 s99, s78, 1
	s_lshl_b32 s99, s99, 5
	s_add_i32 s98, s98, s99
	s_and_b32 s99, s78, 0x18
	s_add_i32 s98, s98, s99
	s_ashr_i32 s3, s98, 31
	s_lshr_b32 s3, s3, 29
	s_add_i32 s7, s98, s3
	s_and_b32 s3, s7, -8
	s_sub_i32 s3, s98, s3
	v_readlane_b32 s10, v239, 29
	s_cmp_gt_i32 s3, -1
	s_mov_b64 s[4:5], -1
	v_readlane_b32 s11, v239, 30
	s_cbranch_scc0 .LBB0_269
	s_lshl_b32 s6, s3, 5
	s_mov_b64 s[4:5], 0

.Lnorm1_regular:
	v_and_b32_e32 v8, 63, v211
	v_lshlrev_b32_e32 v0, 5, v8
	v_lshlrev_b32_e32 v1, 4, v8
	v_lshlrev_b32_e32 v9, 2, v8
	v_xor_b32_e32 v2, 0x4, v9
	v_xor_b32_e32 v3, 0x8, v9
	v_xor_b32_e32 v4, 0x10, v9
	v_xor_b32_e32 v5, 0x20, v9
	v_xor_b32_e32 v6, 0x40, v9
	v_xor_b32_e32 v7, 0x80, v9
	v_readlane_b32 s3, v240, 55
	v_readlane_b32 s6, v239, 10
	s_lshr_b32 s3, s3, 6
	s_lshl_b32 s3, s3, 2
	s_and_b32 s7, s78, 7
	s_lshl_b32 s7, s7, 10
	s_add_i32 s3, s3, s7
	s_lshr_b32 s7, s78, 3
	s_lshl_b32 s7, s7, 5
	s_add_i32 s3, s3, s7
	s_lshl_b32 s6, s6, 3
	s_cmpk_lt_i32 s3, 0x2000
	s_cbranch_scc0 .Lnorm1_end
.Lnorm1_loop:
	s_mov_b32 s8, s3
	s_add_i32 s9, s8, 1
	s_add_i32 s10, s9, 1
	s_add_i32 s11, s10, 1
	s_cmpk_lt_i32 s9, 0x2000
	s_cselect_b32 s9, s9, s3
	s_cmpk_lt_i32 s10, 0x2000
	s_cselect_b32 s10, s10, s3
	s_cmpk_lt_i32 s11, 0x2000
	s_cselect_b32 s11, s11, s3
	s_lshl_b32 s7, s8, 12
	s_add_u32 s4, s46, s7
	s_addc_u32 s5, s47, 0
	s_add_u32 s4, s4, 0x6900000
	s_addc_u32 s5, s5, 0
	global_load_dwordx4 v[16:19], v0, s[4:5]
	global_load_dwordx4 v[20:23], v0, s[4:5] offset:16
	global_load_dwordx4 v[24:27], v0, s[4:5] offset:2048
	global_load_dwordx4 v[28:31], v0, s[4:5] offset:2064
	s_lshl_b32 s7, s9, 12
	s_add_u32 s4, s46, s7
	s_addc_u32 s5, s47, 0
	s_add_u32 s4, s4, 0x6900000
	s_addc_u32 s5, s5, 0
	global_load_dwordx4 v[32:35], v0, s[4:5]
	global_load_dwordx4 v[36:39], v0, s[4:5] offset:16
	global_load_dwordx4 v[40:43], v0, s[4:5] offset:2048
	global_load_dwordx4 v[44:47], v0, s[4:5] offset:2064
	s_lshl_b32 s7, s10, 12
	s_add_u32 s4, s46, s7
	s_addc_u32 s5, s47, 0
	s_add_u32 s4, s4, 0x6900000
	s_addc_u32 s5, s5, 0
	global_load_dwordx4 v[48:51], v0, s[4:5]
	global_load_dwordx4 v[52:55], v0, s[4:5] offset:16
	global_load_dwordx4 v[56:59], v0, s[4:5] offset:2048
	global_load_dwordx4 v[60:63], v0, s[4:5] offset:2064
	s_lshl_b32 s7, s11, 12
	s_add_u32 s4, s46, s7
	s_addc_u32 s5, s47, 0
	s_add_u32 s4, s4, 0x6900000
	s_addc_u32 s5, s5, 0
	global_load_dwordx4 v[64:67], v0, s[4:5]
	global_load_dwordx4 v[68:71], v0, s[4:5] offset:16
	global_load_dwordx4 v[72:75], v0, s[4:5] offset:2048
	global_load_dwordx4 v[76:79], v0, s[4:5] offset:2064
	global_load_dwordx4 v[80:83], v0, s[16:17]
	global_load_dwordx4 v[84:87], v0, s[16:17] offset:16
	global_load_dwordx4 v[88:91], v0, s[16:17] offset:2048
	global_load_dwordx4 v[92:95], v0, s[16:17] offset:2064
	s_sub_i32 s7, s8, 0x1000
	s_lshr_b32 s7, s7, 11
	s_add_i32 s7, s7, 1
	s_cmpk_lt_i32 s8, 0x1000
	s_cselect_b32 s7, 0, s7
	s_mulk_i32 s7, 0x6000
	s_add_i32 s7, s7, 0x0
	s_add_u32 s4, s14, s7
	s_addc_u32 s5, s15, 0
	global_load_dwordx4 v[112:115], v0, s[4:5]
	global_load_dwordx4 v[116:119], v0, s[4:5] offset:16
	global_load_dwordx4 v[120:123], v0, s[4:5] offset:2048
	global_load_dwordx4 v[124:127], v0, s[4:5] offset:2064
	s_add_u32 s4, s4, 0x1000
	s_addc_u32 s5, s5, 0
	global_load_dwordx4 v[96:99], v0, s[4:5]
	global_load_dwordx4 v[100:103], v0, s[4:5] offset:16
	global_load_dwordx4 v[104:107], v0, s[4:5] offset:2048
	global_load_dwordx4 v[108:111], v0, s[4:5] offset:2064
	s_sub_i32 s7, s9, 0x1000
	s_lshr_b32 s7, s7, 11
	s_add_i32 s7, s7, 1
	s_cmpk_lt_i32 s9, 0x1000
	s_cselect_b32 s7, 0, s7
	s_mulk_i32 s7, 0x6000
	s_add_i32 s7, s7, 0x0
	s_add_u32 s4, s14, s7
	s_addc_u32 s5, s15, 0
	global_load_dwordx4 v[144:147], v0, s[4:5]
	global_load_dwordx4 v[148:151], v0, s[4:5] offset:16
	global_load_dwordx4 v[152:155], v0, s[4:5] offset:2048
	global_load_dwordx4 v[156:159], v0, s[4:5] offset:2064
	s_add_u32 s4, s4, 0x1000
	s_addc_u32 s5, s5, 0
	global_load_dwordx4 v[128:131], v0, s[4:5]
	global_load_dwordx4 v[132:135], v0, s[4:5] offset:16
	global_load_dwordx4 v[136:139], v0, s[4:5] offset:2048
	global_load_dwordx4 v[140:143], v0, s[4:5] offset:2064
	s_waitcnt vmcnt(32)
	v_mul_f32_e32 v160, v17, v17
	v_mul_f32_e32 v9, v19, v19
	v_fmac_f32_e32 v160, v16, v16
	v_fmac_f32_e32 v9, v18, v18
	v_add_f32_e32 v160, v160, v9
	v_mul_f32_e32 v8, v21, v21
	v_mul_f32_e32 v9, v23, v23
	v_fmac_f32_e32 v8, v20, v20
	v_fmac_f32_e32 v9, v22, v22
	v_add_f32_e32 v8, v8, v9
	v_add_f32_e32 v160, v160, v8
	v_mul_f32_e32 v8, v25, v25
	v_mul_f32_e32 v9, v27, v27
	v_fmac_f32_e32 v8, v24, v24
	v_fmac_f32_e32 v9, v26, v26
	v_add_f32_e32 v8, v8, v9
	v_add_f32_e32 v160, v160, v8
	v_mul_f32_e32 v8, v29, v29
	v_mul_f32_e32 v9, v31, v31
	v_fmac_f32_e32 v8, v28, v28
	v_fmac_f32_e32 v9, v30, v30
	v_add_f32_e32 v8, v8, v9
	v_add_f32_e32 v160, v160, v8
	s_waitcnt vmcnt(28)
	v_mul_f32_e32 v161, v33, v33
	v_mul_f32_e32 v9, v35, v35
	v_fmac_f32_e32 v161, v32, v32
	v_fmac_f32_e32 v9, v34, v34
	v_add_f32_e32 v161, v161, v9
	v_mul_f32_e32 v8, v37, v37
	v_mul_f32_e32 v9, v39, v39
	v_fmac_f32_e32 v8, v36, v36
	v_fmac_f32_e32 v9, v38, v38
	v_add_f32_e32 v8, v8, v9
	v_add_f32_e32 v161, v161, v8
	v_mul_f32_e32 v8, v41, v41
	v_mul_f32_e32 v9, v43, v43
	v_fmac_f32_e32 v8, v40, v40
	v_fmac_f32_e32 v9, v42, v42
	v_add_f32_e32 v8, v8, v9
	v_add_f32_e32 v161, v161, v8
	v_mul_f32_e32 v8, v45, v45
	v_mul_f32_e32 v9, v47, v47
	v_fmac_f32_e32 v8, v44, v44
	v_fmac_f32_e32 v9, v46, v46
	v_add_f32_e32 v8, v8, v9
	v_add_f32_e32 v161, v161, v8
	s_waitcnt vmcnt(24)
	v_mul_f32_e32 v162, v49, v49
	v_mul_f32_e32 v9, v51, v51
	v_fmac_f32_e32 v162, v48, v48
	v_fmac_f32_e32 v9, v50, v50
	v_add_f32_e32 v162, v162, v9
	v_mul_f32_e32 v8, v53, v53
	v_mul_f32_e32 v9, v55, v55
	v_fmac_f32_e32 v8, v52, v52
	v_fmac_f32_e32 v9, v54, v54
	v_add_f32_e32 v8, v8, v9
	v_add_f32_e32 v162, v162, v8
	v_mul_f32_e32 v8, v57, v57
	v_mul_f32_e32 v9, v59, v59
	v_fmac_f32_e32 v8, v56, v56
	v_fmac_f32_e32 v9, v58, v58
	v_add_f32_e32 v8, v8, v9
	v_add_f32_e32 v162, v162, v8
	v_mul_f32_e32 v8, v61, v61
	v_mul_f32_e32 v9, v63, v63
	v_fmac_f32_e32 v8, v60, v60
	v_fmac_f32_e32 v9, v62, v62
	v_add_f32_e32 v8, v8, v9
	v_add_f32_e32 v162, v162, v8
	s_waitcnt vmcnt(20)
	v_mul_f32_e32 v163, v65, v65
	v_mul_f32_e32 v9, v67, v67
	v_fmac_f32_e32 v163, v64, v64
	v_fmac_f32_e32 v9, v66, v66
	v_add_f32_e32 v163, v163, v9
	v_mul_f32_e32 v8, v69, v69
	v_mul_f32_e32 v9, v71, v71
	v_fmac_f32_e32 v8, v68, v68
	v_fmac_f32_e32 v9, v70, v70
	v_add_f32_e32 v8, v8, v9
	v_add_f32_e32 v163, v163, v8
	v_mul_f32_e32 v8, v73, v73
	v_mul_f32_e32 v9, v75, v75
	v_fmac_f32_e32 v8, v72, v72
	v_fmac_f32_e32 v9, v74, v74
	v_add_f32_e32 v8, v8, v9
	v_add_f32_e32 v163, v163, v8
	v_mul_f32_e32 v8, v77, v77
	v_mul_f32_e32 v9, v79, v79
	v_fmac_f32_e32 v8, v76, v76
	v_fmac_f32_e32 v9, v78, v78
	v_add_f32_e32 v8, v8, v9
	v_add_f32_e32 v163, v163, v8
	ds_bpermute_b32 v8, v2, v160
	ds_bpermute_b32 v9, v2, v161
	ds_bpermute_b32 v10, v2, v162
	ds_bpermute_b32 v11, v2, v163
	s_waitcnt lgkmcnt(3)
	v_add_f32_e32 v160, v160, v8
	s_waitcnt lgkmcnt(2)
	v_add_f32_e32 v161, v161, v9
	s_waitcnt lgkmcnt(1)
	v_add_f32_e32 v162, v162, v10
	s_waitcnt lgkmcnt(0)
	v_add_f32_e32 v163, v163, v11
	ds_bpermute_b32 v8, v3, v160
	ds_bpermute_b32 v9, v3, v161
	ds_bpermute_b32 v10, v3, v162
	ds_bpermute_b32 v11, v3, v163
	s_waitcnt lgkmcnt(3)
	v_add_f32_e32 v160, v160, v8
	s_waitcnt lgkmcnt(2)
	v_add_f32_e32 v161, v161, v9
	s_waitcnt lgkmcnt(1)
	v_add_f32_e32 v162, v162, v10
	s_waitcnt lgkmcnt(0)
	v_add_f32_e32 v163, v163, v11
	ds_bpermute_b32 v8, v4, v160
	ds_bpermute_b32 v9, v4, v161
	ds_bpermute_b32 v10, v4, v162
	ds_bpermute_b32 v11, v4, v163
	s_waitcnt lgkmcnt(3)
	v_add_f32_e32 v160, v160, v8
	s_waitcnt lgkmcnt(2)
	v_add_f32_e32 v161, v161, v9
	s_waitcnt lgkmcnt(1)
	v_add_f32_e32 v162, v162, v10
	s_waitcnt lgkmcnt(0)
	v_add_f32_e32 v163, v163, v11
	ds_bpermute_b32 v8, v5, v160
	ds_bpermute_b32 v9, v5, v161
	ds_bpermute_b32 v10, v5, v162
	ds_bpermute_b32 v11, v5, v163
	s_waitcnt lgkmcnt(3)
	v_add_f32_e32 v160, v160, v8
	s_waitcnt lgkmcnt(2)
	v_add_f32_e32 v161, v161, v9
	s_waitcnt lgkmcnt(1)
	v_add_f32_e32 v162, v162, v10
	s_waitcnt lgkmcnt(0)
	v_add_f32_e32 v163, v163, v11
	ds_bpermute_b32 v8, v6, v160
	ds_bpermute_b32 v9, v6, v161
	ds_bpermute_b32 v10, v6, v162
	ds_bpermute_b32 v11, v6, v163
	s_waitcnt lgkmcnt(3)
	v_add_f32_e32 v160, v160, v8
	s_waitcnt lgkmcnt(2)
	v_add_f32_e32 v161, v161, v9
	s_waitcnt lgkmcnt(1)
	v_add_f32_e32 v162, v162, v10
	s_waitcnt lgkmcnt(0)
	v_add_f32_e32 v163, v163, v11
	ds_bpermute_b32 v8, v7, v160
	ds_bpermute_b32 v9, v7, v161
	ds_bpermute_b32 v10, v7, v162
	ds_bpermute_b32 v11, v7, v163
	s_waitcnt lgkmcnt(3)
	v_add_f32_e32 v160, v160, v8
	s_waitcnt lgkmcnt(2)
	v_add_f32_e32 v161, v161, v9
	s_waitcnt lgkmcnt(1)
	v_add_f32_e32 v162, v162, v10
	s_waitcnt lgkmcnt(0)
	v_add_f32_e32 v163, v163, v11
	s_mov_b32 s7, 0xf800000
	v_fmamk_f32 v160, v160, 0x3a800000, v190
	v_mul_f32_e32 v8, 0x4f800000, v160
	v_cmp_gt_f32_e32 vcc, s7, v160
	s_nop 1
	v_cndmask_b32_e32 v160, v160, v8, vcc
	v_sqrt_f32_e32 v8, v160
	s_nop 0
	v_add_u32_e32 v9, -1, v8
	v_fma_f32 v10, -v9, v8, v160
	v_cmp_ge_f32_e64 s[4:5], 0, v10
	v_add_u32_e32 v10, 1, v8
	s_nop 0
	v_cndmask_b32_e64 v9, v8, v9, s[4:5]
	v_fma_f32 v8, -v10, v8, v160
	v_cmp_lt_f32_e64 s[4:5], 0, v8
	s_nop 1
	v_cndmask_b32_e64 v8, v9, v10, s[4:5]
	v_mul_f32_e32 v9, 0x37800000, v8
	v_cndmask_b32_e32 v8, v8, v9, vcc
	v_cmp_class_f32_e32 vcc, v160, v191
	s_nop 1
	v_cndmask_b32_e32 v160, v8, v160, vcc
	v_div_scale_f32 v8, s[4:5], v160, v160, 1.0
	v_rcp_f32_e32 v9, v8
	s_nop 0
	v_fma_f32 v10, -v8, v9, 1.0
	v_fmac_f32_e32 v9, v10, v9
	v_div_scale_f32 v10, vcc, 1.0, v160, 1.0
	v_mul_f32_e32 v11, v10, v9
	v_fma_f32 v12, -v8, v11, v10
	v_fmac_f32_e32 v11, v12, v9
	v_fma_f32 v8, -v8, v11, v10
	v_div_fmas_f32 v8, v8, v9, v11
	v_div_fixup_f32 v160, v8, v160, 1.0
	s_mov_b32 s7, 0xf800000
	v_fmamk_f32 v161, v161, 0x3a800000, v190
	v_mul_f32_e32 v8, 0x4f800000, v161
	v_cmp_gt_f32_e32 vcc, s7, v161
	s_nop 1
	v_cndmask_b32_e32 v161, v161, v8, vcc
	v_sqrt_f32_e32 v8, v161
	s_nop 0
	v_add_u32_e32 v9, -1, v8
	v_fma_f32 v10, -v9, v8, v161
	v_cmp_ge_f32_e64 s[4:5], 0, v10
	v_add_u32_e32 v10, 1, v8
	s_nop 0
	v_cndmask_b32_e64 v9, v8, v9, s[4:5]
	v_fma_f32 v8, -v10, v8, v161
	v_cmp_lt_f32_e64 s[4:5], 0, v8
	s_nop 1
	v_cndmask_b32_e64 v8, v9, v10, s[4:5]
	v_mul_f32_e32 v9, 0x37800000, v8
	v_cndmask_b32_e32 v8, v8, v9, vcc
	v_cmp_class_f32_e32 vcc, v161, v191
	s_nop 1
	v_cndmask_b32_e32 v161, v8, v161, vcc
	v_div_scale_f32 v8, s[4:5], v161, v161, 1.0
	v_rcp_f32_e32 v9, v8
	s_nop 0
	v_fma_f32 v10, -v8, v9, 1.0
	v_fmac_f32_e32 v9, v10, v9
	v_div_scale_f32 v10, vcc, 1.0, v161, 1.0
	v_mul_f32_e32 v11, v10, v9
	v_fma_f32 v12, -v8, v11, v10
	v_fmac_f32_e32 v11, v12, v9
	v_fma_f32 v8, -v8, v11, v10
	v_div_fmas_f32 v8, v8, v9, v11
	v_div_fixup_f32 v161, v8, v161, 1.0
	s_mov_b32 s7, 0xf800000
	v_fmamk_f32 v162, v162, 0x3a800000, v190
	v_mul_f32_e32 v8, 0x4f800000, v162
	v_cmp_gt_f32_e32 vcc, s7, v162
	s_nop 1
	v_cndmask_b32_e32 v162, v162, v8, vcc
	v_sqrt_f32_e32 v8, v162
	s_nop 0
	v_add_u32_e32 v9, -1, v8
	v_fma_f32 v10, -v9, v8, v162
	v_cmp_ge_f32_e64 s[4:5], 0, v10
	v_add_u32_e32 v10, 1, v8
	s_nop 0
	v_cndmask_b32_e64 v9, v8, v9, s[4:5]
	v_fma_f32 v8, -v10, v8, v162
	v_cmp_lt_f32_e64 s[4:5], 0, v8
	s_nop 1
	v_cndmask_b32_e64 v8, v9, v10, s[4:5]
	v_mul_f32_e32 v9, 0x37800000, v8
	v_cndmask_b32_e32 v8, v8, v9, vcc
	v_cmp_class_f32_e32 vcc, v162, v191
	s_nop 1
	v_cndmask_b32_e32 v162, v8, v162, vcc
	v_div_scale_f32 v8, s[4:5], v162, v162, 1.0
	v_rcp_f32_e32 v9, v8
	s_nop 0
	v_fma_f32 v10, -v8, v9, 1.0
	v_fmac_f32_e32 v9, v10, v9
	v_div_scale_f32 v10, vcc, 1.0, v162, 1.0
	v_mul_f32_e32 v11, v10, v9
	v_fma_f32 v12, -v8, v11, v10
	v_fmac_f32_e32 v11, v12, v9
	v_fma_f32 v8, -v8, v11, v10
	v_div_fmas_f32 v8, v8, v9, v11
	v_div_fixup_f32 v162, v8, v162, 1.0
	s_mov_b32 s7, 0xf800000
	v_fmamk_f32 v163, v163, 0x3a800000, v190
	v_mul_f32_e32 v8, 0x4f800000, v163
	v_cmp_gt_f32_e32 vcc, s7, v163
	s_nop 1
	v_cndmask_b32_e32 v163, v163, v8, vcc
	v_sqrt_f32_e32 v8, v163
	s_nop 0
	v_add_u32_e32 v9, -1, v8
	v_fma_f32 v10, -v9, v8, v163
	v_cmp_ge_f32_e64 s[4:5], 0, v10
	v_add_u32_e32 v10, 1, v8
	s_nop 0
	v_cndmask_b32_e64 v9, v8, v9, s[4:5]
	v_fma_f32 v8, -v10, v8, v163
	v_cmp_lt_f32_e64 s[4:5], 0, v8
	s_nop 1
	v_cndmask_b32_e64 v8, v9, v10, s[4:5]
	v_mul_f32_e32 v9, 0x37800000, v8
	v_cndmask_b32_e32 v8, v8, v9, vcc
	v_cmp_class_f32_e32 vcc, v163, v191
	s_nop 1
	v_cndmask_b32_e32 v163, v8, v163, vcc
	v_div_scale_f32 v8, s[4:5], v163, v163, 1.0
	v_rcp_f32_e32 v9, v8
	s_nop 0
	v_fma_f32 v10, -v8, v9, 1.0
	v_fmac_f32_e32 v9, v10, v9
	v_div_scale_f32 v10, vcc, 1.0, v163, 1.0
	v_mul_f32_e32 v11, v10, v9
	v_fma_f32 v12, -v8, v11, v10
	v_fmac_f32_e32 v11, v12, v9
	v_fma_f32 v8, -v8, v11, v10
	v_div_fmas_f32 v8, v8, v9, v11
	v_div_fixup_f32 v163, v8, v163, 1.0
	s_waitcnt vmcnt(8)
	s_lshl_b32 s7, s8, 11
	s_add_u32 s4, s46, s7
	s_addc_u32 s5, s47, 0
	s_add_u32 s4, s4, 0x8900000
	s_addc_u32 s5, s5, 0
	v_mul_f32_e32 v19, v19, v160
	v_mul_f32_e32 v19, v83, v19
	v_mul_f32_e32 v18, v18, v160
	v_mul_f32_e32 v18, v82, v18
	v_mul_f32_e32 v17, v17, v160
	v_mul_f32_e32 v17, v81, v17
	v_mul_f32_e32 v16, v16, v160
	v_mul_f32_e32 v16, v80, v16
	v_add_f32_e32 v11, 1.0, v99
	v_fma_f32 v19, v11, v19, v115
	v_add_f32_e32 v10, 1.0, v98
	v_fma_f32 v18, v10, v18, v114
	v_add_f32_e32 v9, 1.0, v97
	v_fma_f32 v17, v9, v17, v113
	v_add_f32_e32 v8, 1.0, v96
	v_fma_f32 v16, v8, v16, v112
	v_mul_f32_e32 v23, v23, v160
	v_mul_f32_e32 v23, v87, v23
	v_mul_f32_e32 v22, v22, v160
	v_mul_f32_e32 v22, v86, v22
	v_mul_f32_e32 v21, v21, v160
	v_mul_f32_e32 v21, v85, v21
	v_mul_f32_e32 v20, v20, v160
	v_mul_f32_e32 v20, v84, v20
	v_add_f32_e32 v11, 1.0, v103
	v_fma_f32 v23, v11, v23, v119
	v_add_f32_e32 v10, 1.0, v102
	v_fma_f32 v22, v10, v22, v118
	v_add_f32_e32 v9, 1.0, v101
	v_fma_f32 v21, v9, v21, v117
	v_add_f32_e32 v8, 1.0, v100
	v_fma_f32 v20, v8, v20, v116
	v_cvt_pk_bf16_f32 v16, v16, v17
	v_cvt_pk_bf16_f32 v17, v18, v19
	v_cvt_pk_bf16_f32 v18, v20, v21
	v_cvt_pk_bf16_f32 v19, v22, v23
	global_store_dwordx4 v1, v[16:19], s[4:5]
	v_mul_f32_e32 v27, v27, v160
	v_mul_f32_e32 v27, v91, v27
	v_mul_f32_e32 v26, v26, v160
	v_mul_f32_e32 v26, v90, v26
	v_mul_f32_e32 v25, v25, v160
	v_mul_f32_e32 v25, v89, v25
	v_mul_f32_e32 v24, v24, v160
	v_mul_f32_e32 v24, v88, v24
	v_add_f32_e32 v11, 1.0, v107
	v_fma_f32 v27, v11, v27, v123
	v_add_f32_e32 v10, 1.0, v106
	v_fma_f32 v26, v10, v26, v122
	v_add_f32_e32 v9, 1.0, v105
	v_fma_f32 v25, v9, v25, v121
	v_add_f32_e32 v8, 1.0, v104
	v_fma_f32 v24, v8, v24, v120
	v_mul_f32_e32 v31, v31, v160
	v_mul_f32_e32 v31, v95, v31
	v_mul_f32_e32 v30, v30, v160
	v_mul_f32_e32 v30, v94, v30
	v_mul_f32_e32 v29, v29, v160
	v_mul_f32_e32 v29, v93, v29
	v_mul_f32_e32 v28, v28, v160
	v_mul_f32_e32 v28, v92, v28
	v_add_f32_e32 v11, 1.0, v111
	v_fma_f32 v31, v11, v31, v127
	v_add_f32_e32 v10, 1.0, v110
	v_fma_f32 v30, v10, v30, v126
	v_add_f32_e32 v9, 1.0, v109
	v_fma_f32 v29, v9, v29, v125
	v_add_f32_e32 v8, 1.0, v108
	v_fma_f32 v28, v8, v28, v124
	v_cvt_pk_bf16_f32 v24, v24, v25
	v_cvt_pk_bf16_f32 v25, v26, v27
	v_cvt_pk_bf16_f32 v26, v28, v29
	v_cvt_pk_bf16_f32 v27, v30, v31
	global_store_dwordx4 v1, v[24:27], s[4:5] offset:1024
	s_sub_i32 s7, s10, 0x1000
	s_lshr_b32 s7, s7, 11
	s_add_i32 s7, s7, 1
	s_cmpk_lt_i32 s10, 0x1000
	s_cselect_b32 s7, 0, s7
	s_mulk_i32 s7, 0x6000
	s_add_i32 s7, s7, 0x0
	s_add_u32 s4, s14, s7
	s_addc_u32 s5, s15, 0
	global_load_dwordx4 v[112:115], v0, s[4:5]
	global_load_dwordx4 v[116:119], v0, s[4:5] offset:16
	global_load_dwordx4 v[120:123], v0, s[4:5] offset:2048
	global_load_dwordx4 v[124:127], v0, s[4:5] offset:2064
	s_add_u32 s4, s4, 0x1000
	s_addc_u32 s5, s5, 0
	global_load_dwordx4 v[96:99], v0, s[4:5]
	global_load_dwordx4 v[100:103], v0, s[4:5] offset:16
	global_load_dwordx4 v[104:107], v0, s[4:5] offset:2048
	global_load_dwordx4 v[108:111], v0, s[4:5] offset:2064
	s_waitcnt vmcnt(10)
	s_lshl_b32 s7, s9, 11
	s_add_u32 s4, s46, s7
	s_addc_u32 s5, s47, 0
	s_add_u32 s4, s4, 0x8900000
	s_addc_u32 s5, s5, 0
	v_mul_f32_e32 v35, v35, v161
	v_mul_f32_e32 v35, v83, v35
	v_mul_f32_e32 v34, v34, v161
	v_mul_f32_e32 v34, v82, v34
	v_mul_f32_e32 v33, v33, v161
	v_mul_f32_e32 v33, v81, v33
	v_mul_f32_e32 v32, v32, v161
	v_mul_f32_e32 v32, v80, v32
	v_add_f32_e32 v11, 1.0, v131
	v_fma_f32 v35, v11, v35, v147
	v_add_f32_e32 v10, 1.0, v130
	v_fma_f32 v34, v10, v34, v146
	v_add_f32_e32 v9, 1.0, v129
	v_fma_f32 v33, v9, v33, v145
	v_add_f32_e32 v8, 1.0, v128
	v_fma_f32 v32, v8, v32, v144
	v_mul_f32_e32 v39, v39, v161
	v_mul_f32_e32 v39, v87, v39
	v_mul_f32_e32 v38, v38, v161
	v_mul_f32_e32 v38, v86, v38
	v_mul_f32_e32 v37, v37, v161
	v_mul_f32_e32 v37, v85, v37
	v_mul_f32_e32 v36, v36, v161
	v_mul_f32_e32 v36, v84, v36
	v_add_f32_e32 v11, 1.0, v135
	v_fma_f32 v39, v11, v39, v151
	v_add_f32_e32 v10, 1.0, v134
	v_fma_f32 v38, v10, v38, v150
	v_add_f32_e32 v9, 1.0, v133
	v_fma_f32 v37, v9, v37, v149
	v_add_f32_e32 v8, 1.0, v132
	v_fma_f32 v36, v8, v36, v148
	v_cvt_pk_bf16_f32 v32, v32, v33
	v_cvt_pk_bf16_f32 v33, v34, v35
	v_cvt_pk_bf16_f32 v34, v36, v37
	v_cvt_pk_bf16_f32 v35, v38, v39
	global_store_dwordx4 v1, v[32:35], s[4:5]
	v_mul_f32_e32 v43, v43, v161
	v_mul_f32_e32 v43, v91, v43
	v_mul_f32_e32 v42, v42, v161
	v_mul_f32_e32 v42, v90, v42
	v_mul_f32_e32 v41, v41, v161
	v_mul_f32_e32 v41, v89, v41
	v_mul_f32_e32 v40, v40, v161
	v_mul_f32_e32 v40, v88, v40
	v_add_f32_e32 v11, 1.0, v139
	v_fma_f32 v43, v11, v43, v155
	v_add_f32_e32 v10, 1.0, v138
	v_fma_f32 v42, v10, v42, v154
	v_add_f32_e32 v9, 1.0, v137
	v_fma_f32 v41, v9, v41, v153
	v_add_f32_e32 v8, 1.0, v136
	v_fma_f32 v40, v8, v40, v152
	v_mul_f32_e32 v47, v47, v161
	v_mul_f32_e32 v47, v95, v47
	v_mul_f32_e32 v46, v46, v161
	v_mul_f32_e32 v46, v94, v46
	v_mul_f32_e32 v45, v45, v161
	v_mul_f32_e32 v45, v93, v45
	v_mul_f32_e32 v44, v44, v161
	v_mul_f32_e32 v44, v92, v44
	v_add_f32_e32 v11, 1.0, v143
	v_fma_f32 v47, v11, v47, v159
	v_add_f32_e32 v10, 1.0, v142
	v_fma_f32 v46, v10, v46, v158
	v_add_f32_e32 v9, 1.0, v141
	v_fma_f32 v45, v9, v45, v157
	v_add_f32_e32 v8, 1.0, v140
	v_fma_f32 v44, v8, v44, v156
	v_cvt_pk_bf16_f32 v40, v40, v41
	v_cvt_pk_bf16_f32 v41, v42, v43
	v_cvt_pk_bf16_f32 v42, v44, v45
	v_cvt_pk_bf16_f32 v43, v46, v47
	global_store_dwordx4 v1, v[40:43], s[4:5] offset:1024
	s_sub_i32 s7, s11, 0x1000
	s_lshr_b32 s7, s7, 11
	s_add_i32 s7, s7, 1
	s_cmpk_lt_i32 s11, 0x1000
	s_cselect_b32 s7, 0, s7
	s_mulk_i32 s7, 0x6000
	s_add_i32 s7, s7, 0x0
	s_add_u32 s4, s14, s7
	s_addc_u32 s5, s15, 0
	global_load_dwordx4 v[144:147], v0, s[4:5]
	global_load_dwordx4 v[148:151], v0, s[4:5] offset:16
	global_load_dwordx4 v[152:155], v0, s[4:5] offset:2048
	global_load_dwordx4 v[156:159], v0, s[4:5] offset:2064
	s_add_u32 s4, s4, 0x1000
	s_addc_u32 s5, s5, 0
	global_load_dwordx4 v[128:131], v0, s[4:5]
	global_load_dwordx4 v[132:135], v0, s[4:5] offset:16
	global_load_dwordx4 v[136:139], v0, s[4:5] offset:2048
	global_load_dwordx4 v[140:143], v0, s[4:5] offset:2064
	s_waitcnt vmcnt(10)
	s_lshl_b32 s7, s10, 11
	s_add_u32 s4, s46, s7
	s_addc_u32 s5, s47, 0
	s_add_u32 s4, s4, 0x8900000
	s_addc_u32 s5, s5, 0
	v_mul_f32_e32 v51, v51, v162
	v_mul_f32_e32 v51, v83, v51
	v_mul_f32_e32 v50, v50, v162
	v_mul_f32_e32 v50, v82, v50
	v_mul_f32_e32 v49, v49, v162
	v_mul_f32_e32 v49, v81, v49
	v_mul_f32_e32 v48, v48, v162
	v_mul_f32_e32 v48, v80, v48
	v_add_f32_e32 v11, 1.0, v99
	v_fma_f32 v51, v11, v51, v115
	v_add_f32_e32 v10, 1.0, v98
	v_fma_f32 v50, v10, v50, v114
	v_add_f32_e32 v9, 1.0, v97
	v_fma_f32 v49, v9, v49, v113
	v_add_f32_e32 v8, 1.0, v96
	v_fma_f32 v48, v8, v48, v112
	v_mul_f32_e32 v55, v55, v162
	v_mul_f32_e32 v55, v87, v55
	v_mul_f32_e32 v54, v54, v162
	v_mul_f32_e32 v54, v86, v54
	v_mul_f32_e32 v53, v53, v162
	v_mul_f32_e32 v53, v85, v53
	v_mul_f32_e32 v52, v52, v162
	v_mul_f32_e32 v52, v84, v52
	v_add_f32_e32 v11, 1.0, v103
	v_fma_f32 v55, v11, v55, v119
	v_add_f32_e32 v10, 1.0, v102
	v_fma_f32 v54, v10, v54, v118
	v_add_f32_e32 v9, 1.0, v101
	v_fma_f32 v53, v9, v53, v117
	v_add_f32_e32 v8, 1.0, v100
	v_fma_f32 v52, v8, v52, v116
	v_cvt_pk_bf16_f32 v48, v48, v49
	v_cvt_pk_bf16_f32 v49, v50, v51
	v_cvt_pk_bf16_f32 v50, v52, v53
	v_cvt_pk_bf16_f32 v51, v54, v55
	global_store_dwordx4 v1, v[48:51], s[4:5]
	v_mul_f32_e32 v59, v59, v162
	v_mul_f32_e32 v59, v91, v59
	v_mul_f32_e32 v58, v58, v162
	v_mul_f32_e32 v58, v90, v58
	v_mul_f32_e32 v57, v57, v162
	v_mul_f32_e32 v57, v89, v57
	v_mul_f32_e32 v56, v56, v162
	v_mul_f32_e32 v56, v88, v56
	v_add_f32_e32 v11, 1.0, v107
	v_fma_f32 v59, v11, v59, v123
	v_add_f32_e32 v10, 1.0, v106
	v_fma_f32 v58, v10, v58, v122
	v_add_f32_e32 v9, 1.0, v105
	v_fma_f32 v57, v9, v57, v121
	v_add_f32_e32 v8, 1.0, v104
	v_fma_f32 v56, v8, v56, v120
	v_mul_f32_e32 v63, v63, v162
	v_mul_f32_e32 v63, v95, v63
	v_mul_f32_e32 v62, v62, v162
	v_mul_f32_e32 v62, v94, v62
	v_mul_f32_e32 v61, v61, v162
	v_mul_f32_e32 v61, v93, v61
	v_mul_f32_e32 v60, v60, v162
	v_mul_f32_e32 v60, v92, v60
	v_add_f32_e32 v11, 1.0, v111
	v_fma_f32 v63, v11, v63, v127
	v_add_f32_e32 v10, 1.0, v110
	v_fma_f32 v62, v10, v62, v126
	v_add_f32_e32 v9, 1.0, v109
	v_fma_f32 v61, v9, v61, v125
	v_add_f32_e32 v8, 1.0, v108
	v_fma_f32 v60, v8, v60, v124
	v_cvt_pk_bf16_f32 v56, v56, v57
	v_cvt_pk_bf16_f32 v57, v58, v59
	v_cvt_pk_bf16_f32 v58, v60, v61
	v_cvt_pk_bf16_f32 v59, v62, v63
	global_store_dwordx4 v1, v[56:59], s[4:5] offset:1024
	s_waitcnt vmcnt(2)
	s_lshl_b32 s7, s11, 11
	s_add_u32 s4, s46, s7
	s_addc_u32 s5, s47, 0
	s_add_u32 s4, s4, 0x8900000
	s_addc_u32 s5, s5, 0
	v_mul_f32_e32 v67, v67, v163
	v_mul_f32_e32 v67, v83, v67
	v_mul_f32_e32 v66, v66, v163
	v_mul_f32_e32 v66, v82, v66
	v_mul_f32_e32 v65, v65, v163
	v_mul_f32_e32 v65, v81, v65
	v_mul_f32_e32 v64, v64, v163
	v_mul_f32_e32 v64, v80, v64
	v_add_f32_e32 v11, 1.0, v131
	v_fma_f32 v67, v11, v67, v147
	v_add_f32_e32 v10, 1.0, v130
	v_fma_f32 v66, v10, v66, v146
	v_add_f32_e32 v9, 1.0, v129
	v_fma_f32 v65, v9, v65, v145
	v_add_f32_e32 v8, 1.0, v128
	v_fma_f32 v64, v8, v64, v144
	v_mul_f32_e32 v71, v71, v163
	v_mul_f32_e32 v71, v87, v71
	v_mul_f32_e32 v70, v70, v163
	v_mul_f32_e32 v70, v86, v70
	v_mul_f32_e32 v69, v69, v163
	v_mul_f32_e32 v69, v85, v69
	v_mul_f32_e32 v68, v68, v163
	v_mul_f32_e32 v68, v84, v68
	v_add_f32_e32 v11, 1.0, v135
	v_fma_f32 v71, v11, v71, v151
	v_add_f32_e32 v10, 1.0, v134
	v_fma_f32 v70, v10, v70, v150
	v_add_f32_e32 v9, 1.0, v133
	v_fma_f32 v69, v9, v69, v149
	v_add_f32_e32 v8, 1.0, v132
	v_fma_f32 v68, v8, v68, v148
	v_cvt_pk_bf16_f32 v64, v64, v65
	v_cvt_pk_bf16_f32 v65, v66, v67
	v_cvt_pk_bf16_f32 v66, v68, v69
	v_cvt_pk_bf16_f32 v67, v70, v71
	global_store_dwordx4 v1, v[64:67], s[4:5]
	v_mul_f32_e32 v75, v75, v163
	v_mul_f32_e32 v75, v91, v75
	v_mul_f32_e32 v74, v74, v163
	v_mul_f32_e32 v74, v90, v74
	v_mul_f32_e32 v73, v73, v163
	v_mul_f32_e32 v73, v89, v73
	v_mul_f32_e32 v72, v72, v163
	v_mul_f32_e32 v72, v88, v72
	v_add_f32_e32 v11, 1.0, v139
	v_fma_f32 v75, v11, v75, v155
	v_add_f32_e32 v10, 1.0, v138
	v_fma_f32 v74, v10, v74, v154
	v_add_f32_e32 v9, 1.0, v137
	v_fma_f32 v73, v9, v73, v153
	v_add_f32_e32 v8, 1.0, v136
	v_fma_f32 v72, v8, v72, v152
	v_mul_f32_e32 v79, v79, v163
	v_mul_f32_e32 v79, v95, v79
	v_mul_f32_e32 v78, v78, v163
	v_mul_f32_e32 v78, v94, v78
	v_mul_f32_e32 v77, v77, v163
	v_mul_f32_e32 v77, v93, v77
	v_mul_f32_e32 v76, v76, v163
	v_mul_f32_e32 v76, v92, v76
	v_add_f32_e32 v11, 1.0, v143
	v_fma_f32 v79, v11, v79, v159
	v_add_f32_e32 v10, 1.0, v142
	v_fma_f32 v78, v10, v78, v158
	v_add_f32_e32 v9, 1.0, v141
	v_fma_f32 v77, v9, v77, v157
	v_add_f32_e32 v8, 1.0, v140
	v_fma_f32 v76, v8, v76, v156
	v_cvt_pk_bf16_f32 v72, v72, v73
	v_cvt_pk_bf16_f32 v73, v74, v75
	v_cvt_pk_bf16_f32 v74, v76, v77
	v_cvt_pk_bf16_f32 v75, v78, v79
	global_store_dwordx4 v1, v[72:75], s[4:5] offset:1024
	s_lshl_b32 s7, s6, 2
	s_add_i32 s3, s3, s7
	s_cmpk_lt_i32 s3, 0x2000
	s_cbranch_scc1 .Lnorm1_loop
